# v50_a3_value_tile_loads_issued_early_in_gating
# baseline (speedup 1.0000x reference)
; #define LAS __attribute__((address_space(3)))
; __device__ __forceinline__ void gla_bcum(KArgs a, int tid, int t0, int h, LAS float* segtot, LAS float* glrs, float (&bc)[32], float& tot) {
;     const int d = tid & 127, seg = __builtin_amdgcn_readfirstlane(tid >> 7), col = h * 128 + d;
;     const float* glr = (const float*)(a->ws + WS_GLR);
;     float w2r[16];
; #pragma unroll
;     for (int j = 0; j < 16; ++j) w2r[j] = a->gate_w2[j * 512 + col];
;     const float bias = a->gate_b[col];
;     *(LAS f32x4*)(glrs + tid * 4) = *(const f32x4*)(glr + (size_t)t0 * 16 + tid * 4);
;     __syncthreads();
;     float run = 0.f;
; #pragma unroll
;     for (int r = 0; r < 32; ++r) { const LAS f32x4* gp = (const LAS f32x4*)(glrs + (seg * 32 + r) * 16);
;         float z = bias;
; #pragma unroll
;         for (int q = 0; q < 4; ++q) { const f32x4 g = gp[q]; z += g[0] * w2r[4 * q] + g[1] * w2r[4 * q + 1] + g[2] * w2r[4 * q + 2] + g[3] * w2r[4 * q + 3]; }
;         const float la = (fminf(z, 0.f) - __logf(1.0f + __expf(-fabsf(z)))) * (1.0f / 16.0f);
;         run += la; bc[r] = run; }
.LBB0_478:
	s_bfe_u32 s1, s42, 0x20005
	s_lshl_b32 s8, s1, 9
	v_lshl_or_b32 v0, v88, 2, s8
	v_lshl_add_u64 v[16:17], s[16:17], 0, v[0:1]
	v_add_co_u32_e32 v18, vcc, s25, v16
	s_and_b32 s0, s42, 31
	s_nop 0
	v_addc_co_u32_e32 v19, vcc, 0, v17, vcc
	v_add_co_u32_e32 v2, vcc, s26, v16
	s_lshl_b32 s6, s42, 5
	s_nop 0
	v_addc_co_u32_e32 v3, vcc, 0, v17, vcc
	v_add_co_u32_e32 v24, vcc, s27, v16
	s_and_b32 s6, s6, 0xfffff000
	s_lshl_b32 s7, s0, 7
	v_addc_co_u32_e32 v25, vcc, 0, v17, vcc
	s_or_b32 s44, s6, s7
	v_add_co_u32_e32 v4, vcc, s28, v16
	s_ashr_i32 s45, s44, 31
	s_nop 0
	v_addc_co_u32_e32 v5, vcc, 0, v17, vcc
	s_lshl_b64 s[6:7], s[44:45], 6
	v_add_co_u32_e32 v26, vcc, s30, v16
	v_lshl_add_u64 v[6:7], v[90:91], 0, s[6:7]
	s_nop 0
	v_addc_co_u32_e32 v27, vcc, 0, v17, vcc
	s_barrier
	global_load_dwordx4 v[20:23], v[6:7], off
	global_load_dword v12, v0, s[16:17]
	global_load_dword v15, v0, s[16:17] offset:2048
	global_load_dword v14, v[2:3], off offset:-4096
	global_load_dword v11, v[2:3], off
	global_load_dword v13, v[2:3], off offset:2048
	global_load_dword v9, v[4:5], off offset:-4096
	s_nop 0
	global_load_dword v3, v[4:5], off
	global_load_dword v7, v[4:5], off offset:2048
	s_nop 0
	global_load_dword v5, v[26:27], off offset:-4096
	global_load_dword v2, v[26:27], off
	global_load_dword v4, v[26:27], off offset:2048
	v_add_co_u32_e32 v26, vcc, s29, v16
	v_readfirstlane_b32 s36, v84
	s_nop 0
	v_addc_co_u32_e32 v27, vcc, 0, v17, vcc
	v_add_co_u32_e32 v28, vcc, s31, v16
	s_ashr_i32 s9, s36, 7
	s_nop 0
	v_addc_co_u32_e32 v29, vcc, 0, v17, vcc
	global_load_dword v6, v[28:29], off
	global_load_dword v17, v[18:19], off offset:2048
	global_load_dword v16, v[24:25], off offset:2048
	global_load_dword v10, v[26:27], off offset:2048
	global_load_dword v8, v[28:29], off offset:2048
	s_nop 0
	global_load_dword v19, v0, s[18:19]
	s_lshl_b32 s98, s1, 8
	s_mov_b32 s99, 0
	v_lshl_add_u64 v[82:83], v[92:93], 0, s[98:99]
	s_lshl_b32 s6, s9, 11
	s_add_i32 s6, s6, 0
	s_add_i32 s6, s6, 0x11000
	v_mov_b32_e32 v0, s6
	v_mov_b32_e32 v111, v1
	s_waitcnt vmcnt(17)
	ds_write_b128 v117, v[20:23]
	s_waitcnt lgkmcnt(0)
	s_barrier
	ds_read_b128 v[20:23], v0
	ds_read_b128 v[24:27], v0 offset:16
	ds_read_b128 v[28:31], v0 offset:32
	ds_read_b128 v[32:35], v0 offset:48
	ds_read_b128 v[36:39], v0 offset:64
	ds_read_b128 v[40:43], v0 offset:80
	s_waitcnt lgkmcnt(5)
	s_waitcnt vmcnt(15)
	v_mul_f32_e32 v18, v15, v21
	s_waitcnt lgkmcnt(4)
	s_waitcnt vmcnt(12)
	v_mul_f32_e32 v21, v13, v25
	v_fmac_f32_e32 v18, v12, v20
	s_waitcnt lgkmcnt(3)
	s_waitcnt vmcnt(9)
	v_mul_f32_e32 v25, v7, v29
	v_fmac_f32_e32 v21, v11, v24
	v_fmac_f32_e32 v18, v14, v22
	s_waitcnt lgkmcnt(2)
	s_waitcnt vmcnt(6)
	v_mul_f32_e32 v29, v4, v33
	v_fmac_f32_e32 v25, v3, v28
	v_fmac_f32_e32 v21, v9, v26
	v_fmac_f32_e32 v29, v2, v32
	s_waitcnt vmcnt(4)
	v_fmac_f32_e32 v18, v17, v23
	v_fmac_f32_e32 v25, v5, v30
	s_waitcnt vmcnt(3)
	v_fmac_f32_e32 v21, v16, v27
	v_fmac_f32_e32 v29, v6, v34
	s_waitcnt vmcnt(0)
	v_add_f32_e32 v18, v19, v18
	v_fmac_f32_e32 v25, v10, v31
	v_add_f32_e32 v18, v18, v21
	v_fmac_f32_e32 v29, v8, v35
	v_add_f32_e32 v18, v18, v25
	v_add_f32_e32 v18, v18, v29
	v_mul_f32_e64 v20, |v18|, s33
	v_exp_f32_e32 v20, v20
	s_waitcnt lgkmcnt(1)
	v_mul_f32_e32 v33, v15, v37
	s_waitcnt lgkmcnt(0)
	v_mul_f32_e32 v24, v13, v41
	v_fmac_f32_e32 v33, v12, v36
	v_add_f32_e32 v20, 1.0, v20
	v_fmac_f32_e32 v33, v14, v38
	v_fmac_f32_e32 v24, v11, v40
	v_log_f32_e32 v28, v20
	v_fmac_f32_e32 v33, v17, v39
	v_fmac_f32_e32 v24, v9, v42
	v_add_f32_e32 v25, v19, v33
	v_mul_f32_e32 v20, 0x3f317217, v28
	v_fma_f32 v29, v28, s35, -v20
	ds_read_b128 v[20:23], v0 offset:96
	v_fmac_f32_e32 v24, v16, v43
	v_add_f32_e32 v30, v25, v24
	ds_read_b128 v[24:27], v0 offset:112
	v_fmac_f32_e32 v29, 0x3377d1cf, v28
	s_waitcnt lgkmcnt(1)
	v_mul_f32_e32 v21, v7, v21
	v_fmac_f32_e32 v21, v3, v20
	v_fmac_f32_e32 v21, v5, v22
	v_fmac_f32_e32 v21, v10, v23
	v_add_f32_e32 v20, v30, v21
	s_waitcnt lgkmcnt(0)
	v_mul_f32_e32 v21, v4, v25
	v_fmac_f32_e32 v21, v2, v24
	v_fmac_f32_e32 v21, v6, v26
	v_fmac_f32_e32 v21, v8, v27
	v_add_f32_e32 v20, v20, v21
	v_mul_f32_e64 v21, |v20|, s33
	v_exp_f32_e32 v21, v21
	v_fmac_f32_e32 v29, 0x3f317217, v28
	v_add_f32_e32 v21, 1.0, v21
	v_mov_b32_e32 v22, v29
	v_min_f32_e32 v18, 0, v18
	v_log_f32_e32 v28, v21
	v_sub_f32_e32 v18, v18, v22
	v_min_f32_e32 v29, 0, v20
	ds_read_b128 v[20:23], v0 offset:128
	v_mul_f32_e32 v24, 0x3f317217, v28
	v_fma_f32 v30, v28, s35, -v24
	ds_read_b128 v[24:27], v0 offset:144
	v_fmac_f32_e32 v30, 0x3377d1cf, v28
	s_waitcnt lgkmcnt(1)
	v_mul_f32_e32 v21, v15, v21
	v_fmac_f32_e32 v21, v12, v20
	v_fmac_f32_e32 v21, v14, v22
	v_fmac_f32_e32 v21, v17, v23
	v_add_f32_e32 v31, v19, v21
	s_waitcnt lgkmcnt(0)
	v_mul_f32_e32 v25, v13, v25
	ds_read_b128 v[20:23], v0 offset:160
	v_fmac_f32_e32 v25, v11, v24
	v_fmac_f32_e32 v25, v9, v26
	v_fmac_f32_e32 v25, v16, v27
	v_add_f32_e32 v31, v31, v25
	ds_read_b128 v[24:27], v0 offset:176
	s_waitcnt lgkmcnt(1)
	v_mul_f32_e32 v21, v7, v21
	v_fmac_f32_e32 v21, v3, v20
	v_fmac_f32_e32 v21, v5, v22
	v_fmac_f32_e32 v21, v10, v23
	v_add_f32_e32 v20, v31, v21
	s_waitcnt lgkmcnt(0)
	v_mul_f32_e32 v21, v4, v25
	v_fmac_f32_e32 v21, v2, v24
	v_fmac_f32_e32 v21, v6, v26
	v_fmac_f32_e32 v21, v8, v27
	v_add_f32_e32 v21, v20, v21
	v_mul_f32_e64 v20, |v21|, s33
	v_exp_f32_e32 v20, v20
	v_fmac_f32_e32 v30, 0x3f317217, v28
	v_add_f32_e32 v20, 1.0, v20
	v_mov_b32_e32 v22, v30
	v_min_f32_e32 v21, 0, v21
	v_log_f32_e32 v30, v20
	v_sub_f32_e32 v20, v29, v22
	ds_read_b128 v[22:25], v0 offset:192
	v_fma_f32 v18, v18, s47, 0
	v_mul_f32_e32 v26, 0x3f317217, v30
	v_fma_f32 v31, v30, s35, -v26
	ds_read_b128 v[26:29], v0 offset:208
	s_waitcnt lgkmcnt(1)
; #define LAS __attribute__((address_space(3)))
; __device__ __forceinline__ void gla_bcum(KArgs a, int tid, int t0, int h, LAS float* segtot, LAS float* glrs, float (&bc)[32], float& tot) {
;     ...
;     for (int r = 0; r < 32; ++r) { const LAS f32x4* gp = (const LAS f32x4*)(glrs + (seg * 32 + r) * 16);
;         float z = bias;
; #pragma unroll
;         for (int q = 0; q < 4; ++q) { const f32x4 g = gp[q]; z += g[0] * w2r[4 * q] + g[1] * w2r[4 * q + 1] + g[2] * w2r[4 * q + 2] + g[3] * w2r[4 * q + 3]; }
;         const float la = (fminf(z, 0.f) - __logf(1.0f + __expf(-fabsf(z)))) * (1.0f / 16.0f);
;         run += la; bc[r] = run; }
	v_mul_f32_e32 v23, v15, v23
	v_fmac_f32_e32 v23, v12, v22
	v_fmac_f32_e32 v23, v14, v24
	v_fmac_f32_e32 v23, v17, v25
	v_add_f32_e32 v32, v19, v23
	s_waitcnt lgkmcnt(0)
	v_mul_f32_e32 v27, v13, v27
	ds_read_b128 v[22:25], v0 offset:224
	v_fmac_f32_e32 v27, v11, v26
	v_fmac_f32_e32 v27, v9, v28
	v_fmac_f32_e32 v27, v16, v29
	v_add_f32_e32 v32, v32, v27
	ds_read_b128 v[26:29], v0 offset:240
	s_waitcnt lgkmcnt(1)
	v_mul_f32_e32 v23, v7, v23
	v_fmac_f32_e32 v23, v3, v22
	v_fmac_f32_e32 v23, v5, v24
	v_fmac_f32_e32 v23, v10, v25
	v_add_f32_e32 v22, v32, v23
	s_waitcnt lgkmcnt(0)
	v_mul_f32_e32 v23, v4, v27
	v_fmac_f32_e32 v23, v2, v26
	v_fmac_f32_e32 v23, v6, v28
	v_fmac_f32_e32 v23, v8, v29
	v_add_f32_e32 v22, v22, v23
	v_mul_f32_e64 v23, |v22|, s33
	v_exp_f32_e32 v23, v23
	v_fmac_f32_e32 v31, 0x3377d1cf, v30
	v_fmac_f32_e32 v31, 0x3f317217, v30
	v_add_f32_e32 v23, 1.0, v23
	v_mov_b32_e32 v24, v31
	v_sub_f32_e32 v21, v21, v24
	v_log_f32_e32 v30, v23
	v_min_f32_e32 v31, 0, v22
	ds_read_b128 v[22:25], v0 offset:256
	v_fmamk_f32 v20, v20, 0x3d800000, v18
	v_mul_f32_e32 v26, 0x3f317217, v30
	v_fma_f32 v32, v30, s35, -v26
	ds_read_b128 v[26:29], v0 offset:272
	s_waitcnt lgkmcnt(1)
	v_mul_f32_e32 v23, v15, v23
	v_fmac_f32_e32 v23, v12, v22
	v_fmac_f32_e32 v23, v14, v24
	v_fmac_f32_e32 v23, v17, v25
	v_add_f32_e32 v33, v19, v23
	s_waitcnt lgkmcnt(0)
	v_mul_f32_e32 v27, v13, v27
	ds_read_b128 v[22:25], v0 offset:288
	v_fmac_f32_e32 v27, v11, v26
	v_fmac_f32_e32 v27, v9, v28
	v_fmac_f32_e32 v27, v16, v29
	v_add_f32_e32 v33, v33, v27
	ds_read_b128 v[26:29], v0 offset:304
	s_waitcnt lgkmcnt(1)
	v_mul_f32_e32 v23, v7, v23
	v_fmac_f32_e32 v23, v3, v22
	v_fmac_f32_e32 v23, v5, v24
	v_fmac_f32_e32 v23, v10, v25
	v_add_f32_e32 v22, v33, v23
	s_waitcnt lgkmcnt(0)
	v_mul_f32_e32 v23, v4, v27
	v_fmac_f32_e32 v23, v2, v26
	v_fmac_f32_e32 v23, v6, v28
	v_fmac_f32_e32 v23, v8, v29
	v_add_f32_e32 v23, v22, v23
	v_mul_f32_e64 v22, |v23|, s33
	v_exp_f32_e32 v22, v22
	v_fmac_f32_e32 v32, 0x3377d1cf, v30
	v_fmac_f32_e32 v32, 0x3f317217, v30
	v_add_f32_e32 v22, 1.0, v22
	v_mov_b32_e32 v24, v32
	v_min_f32_e32 v23, 0, v23
	v_log_f32_e32 v32, v22
	v_sub_f32_e32 v22, v31, v24
	ds_read_b128 v[24:27], v0 offset:320
	v_fmamk_f32 v21, v21, 0x3d800000, v20
	v_mul_f32_e32 v28, 0x3f317217, v32
	v_fma_f32 v33, v32, s35, -v28
	ds_read_b128 v[28:31], v0 offset:336
	s_waitcnt lgkmcnt(1)
	v_mul_f32_e32 v25, v15, v25
	v_fmac_f32_e32 v25, v12, v24
	v_fmac_f32_e32 v25, v14, v26
	v_fmac_f32_e32 v25, v17, v27
	v_add_f32_e32 v34, v19, v25
	s_waitcnt lgkmcnt(0)
	v_mul_f32_e32 v29, v13, v29
	ds_read_b128 v[24:27], v0 offset:352
	v_fmac_f32_e32 v29, v11, v28
	v_fmac_f32_e32 v29, v9, v30
	v_fmac_f32_e32 v29, v16, v31
	v_add_f32_e32 v34, v34, v29
	ds_read_b128 v[28:31], v0 offset:368
	s_waitcnt lgkmcnt(1)
	v_mul_f32_e32 v25, v7, v25
	v_fmac_f32_e32 v25, v3, v24
	v_fmac_f32_e32 v25, v5, v26
	v_fmac_f32_e32 v25, v10, v27
	v_add_f32_e32 v24, v34, v25
	s_waitcnt lgkmcnt(0)
	v_mul_f32_e32 v25, v4, v29
	v_fmac_f32_e32 v25, v2, v28
	v_fmac_f32_e32 v25, v6, v30
	v_fmac_f32_e32 v25, v8, v31
	v_add_f32_e32 v24, v24, v25
	v_mul_f32_e64 v25, |v24|, s33
	v_exp_f32_e32 v25, v25
	v_fmac_f32_e32 v33, 0x3377d1cf, v32
	v_fmac_f32_e32 v33, 0x3f317217, v32
	v_add_f32_e32 v25, 1.0, v25
	v_mov_b32_e32 v26, v33
	v_sub_f32_e32 v23, v23, v26
	v_log_f32_e32 v32, v25
	v_min_f32_e32 v33, 0, v24
	ds_read_b128 v[24:27], v0 offset:384
	v_fmamk_f32 v22, v22, 0x3d800000, v21
	v_mul_f32_e32 v28, 0x3f317217, v32
	v_fma_f32 v34, v32, s35, -v28
	ds_read_b128 v[28:31], v0 offset:400
	s_waitcnt lgkmcnt(1)
	v_mul_f32_e32 v25, v15, v25
	v_fmac_f32_e32 v25, v12, v24
	v_fmac_f32_e32 v25, v14, v26
	v_fmac_f32_e32 v25, v17, v27
	v_add_f32_e32 v35, v19, v25
	s_waitcnt lgkmcnt(0)
	v_mul_f32_e32 v29, v13, v29
	ds_read_b128 v[24:27], v0 offset:416
	v_fmac_f32_e32 v29, v11, v28
	v_fmac_f32_e32 v29, v9, v30
	v_fmac_f32_e32 v29, v16, v31
	v_add_f32_e32 v35, v35, v29
	ds_read_b128 v[28:31], v0 offset:432
	s_waitcnt lgkmcnt(1)
	v_mul_f32_e32 v25, v7, v25
	v_fmac_f32_e32 v25, v3, v24
	v_fmac_f32_e32 v25, v5, v26
	v_fmac_f32_e32 v25, v10, v27
	v_add_f32_e32 v24, v35, v25
	s_waitcnt lgkmcnt(0)
	v_mul_f32_e32 v25, v4, v29
	v_fmac_f32_e32 v25, v2, v28
	v_fmac_f32_e32 v25, v6, v30
	v_fmac_f32_e32 v25, v8, v31
	v_add_f32_e32 v25, v24, v25
	v_mul_f32_e64 v24, |v25|, s33
	v_exp_f32_e32 v24, v24
	v_fmac_f32_e32 v34, 0x3377d1cf, v32
	v_fmac_f32_e32 v34, 0x3f317217, v32
	v_add_f32_e32 v24, 1.0, v24
	v_mov_b32_e32 v26, v34
	v_min_f32_e32 v25, 0, v25
	v_log_f32_e32 v34, v24
	v_sub_f32_e32 v24, v33, v26
	ds_read_b128 v[26:29], v0 offset:448
	v_fmamk_f32 v23, v23, 0x3d800000, v22
	v_mul_f32_e32 v30, 0x3f317217, v34
	v_fma_f32 v35, v34, s35, -v30
	ds_read_b128 v[30:33], v0 offset:464
	s_waitcnt lgkmcnt(1)
	v_mul_f32_e32 v27, v15, v27
	v_fmac_f32_e32 v27, v12, v26
	v_fmac_f32_e32 v27, v14, v28
	v_fmac_f32_e32 v27, v17, v29
	v_add_f32_e32 v36, v19, v27
	s_waitcnt lgkmcnt(0)
	v_mul_f32_e32 v31, v13, v31
	ds_read_b128 v[26:29], v0 offset:480
	v_fmac_f32_e32 v31, v11, v30
	v_fmac_f32_e32 v31, v9, v32
	v_fmac_f32_e32 v31, v16, v33
	v_add_f32_e32 v36, v36, v31
	ds_read_b128 v[30:33], v0 offset:496
	s_waitcnt lgkmcnt(1)
	v_mul_f32_e32 v27, v7, v27
	v_fmac_f32_e32 v27, v3, v26
	v_fmac_f32_e32 v27, v5, v28
	v_fmac_f32_e32 v27, v10, v29
	v_add_f32_e32 v26, v36, v27
	s_waitcnt lgkmcnt(0)
; #define LAS __attribute__((address_space(3)))
; __device__ __forceinline__ void gla_bcum(KArgs a, int tid, int t0, int h, LAS float* segtot, LAS float* glrs, float (&bc)[32], float& tot) {
;     ...
;     for (int r = 0; r < 32; ++r) { const LAS f32x4* gp = (const LAS f32x4*)(glrs + (seg * 32 + r) * 16);
;         float z = bias;
; #pragma unroll
;         for (int q = 0; q < 4; ++q) { const f32x4 g = gp[q]; z += g[0] * w2r[4 * q] + g[1] * w2r[4 * q + 1] + g[2] * w2r[4 * q + 2] + g[3] * w2r[4 * q + 3]; }
;         const float la = (fminf(z, 0.f) - __logf(1.0f + __expf(-fabsf(z)))) * (1.0f / 16.0f);
;         run += la; bc[r] = run; }
	v_mul_f32_e32 v27, v4, v31
	v_fmac_f32_e32 v27, v2, v30
	v_fmac_f32_e32 v27, v6, v32
	v_fmac_f32_e32 v27, v8, v33
	v_add_f32_e32 v26, v26, v27
	v_mul_f32_e64 v27, |v26|, s33
	v_exp_f32_e32 v27, v27
	v_fmac_f32_e32 v35, 0x3377d1cf, v34
	v_fmac_f32_e32 v35, 0x3f317217, v34
	v_add_f32_e32 v27, 1.0, v27
	v_mov_b32_e32 v28, v35
	v_sub_f32_e32 v25, v25, v28
	v_log_f32_e32 v34, v27
	v_min_f32_e32 v35, 0, v26
	ds_read_b128 v[26:29], v0 offset:512
	v_fmamk_f32 v24, v24, 0x3d800000, v23
	v_mul_f32_e32 v30, 0x3f317217, v34
	v_fma_f32 v36, v34, s35, -v30
	ds_read_b128 v[30:33], v0 offset:528
	s_waitcnt lgkmcnt(1)
	v_mul_f32_e32 v27, v15, v27
	v_fmac_f32_e32 v27, v12, v26
	v_fmac_f32_e32 v27, v14, v28
	v_fmac_f32_e32 v27, v17, v29
	v_add_f32_e32 v37, v19, v27
	s_waitcnt lgkmcnt(0)
	v_mul_f32_e32 v31, v13, v31
	ds_read_b128 v[26:29], v0 offset:544
	v_fmac_f32_e32 v31, v11, v30
	v_fmac_f32_e32 v31, v9, v32
	v_fmac_f32_e32 v31, v16, v33
	v_add_f32_e32 v37, v37, v31
	ds_read_b128 v[30:33], v0 offset:560
	s_waitcnt lgkmcnt(1)
	v_mul_f32_e32 v27, v7, v27
	v_fmac_f32_e32 v27, v3, v26
	v_fmac_f32_e32 v27, v5, v28
	v_fmac_f32_e32 v27, v10, v29
	v_add_f32_e32 v26, v37, v27
	s_waitcnt lgkmcnt(0)
	v_mul_f32_e32 v27, v4, v31
	v_fmac_f32_e32 v27, v2, v30
	v_fmac_f32_e32 v27, v6, v32
	v_fmac_f32_e32 v27, v8, v33
	v_add_f32_e32 v27, v26, v27
	v_mul_f32_e64 v26, |v27|, s33
	v_exp_f32_e32 v26, v26
	v_fmac_f32_e32 v36, 0x3377d1cf, v34
	v_fmac_f32_e32 v36, 0x3f317217, v34
	v_add_f32_e32 v26, 1.0, v26
	v_mov_b32_e32 v28, v36
	v_min_f32_e32 v27, 0, v27
	v_log_f32_e32 v36, v26
	v_sub_f32_e32 v26, v35, v28
	ds_read_b128 v[28:31], v0 offset:576
	v_fmamk_f32 v25, v25, 0x3d800000, v24
	v_mul_f32_e32 v32, 0x3f317217, v36
	v_fma_f32 v37, v36, s35, -v32
	ds_read_b128 v[32:35], v0 offset:592
	s_waitcnt lgkmcnt(1)
	v_mul_f32_e32 v29, v15, v29
	v_fmac_f32_e32 v29, v12, v28
	v_fmac_f32_e32 v29, v14, v30
	v_fmac_f32_e32 v29, v17, v31
	v_add_f32_e32 v38, v19, v29
	s_waitcnt lgkmcnt(0)
	v_mul_f32_e32 v33, v13, v33
	ds_read_b128 v[28:31], v0 offset:608
	v_fmac_f32_e32 v33, v11, v32
	v_fmac_f32_e32 v33, v9, v34
	v_fmac_f32_e32 v33, v16, v35
	v_add_f32_e32 v38, v38, v33
	ds_read_b128 v[32:35], v0 offset:624
	s_waitcnt lgkmcnt(1)
	v_mul_f32_e32 v29, v7, v29
	v_fmac_f32_e32 v29, v3, v28
	v_fmac_f32_e32 v29, v5, v30
	v_fmac_f32_e32 v29, v10, v31
	v_add_f32_e32 v28, v38, v29
	s_waitcnt lgkmcnt(0)
	v_mul_f32_e32 v29, v4, v33
	v_fmac_f32_e32 v29, v2, v32
	v_fmac_f32_e32 v29, v6, v34
	v_fmac_f32_e32 v29, v8, v35
	v_add_f32_e32 v28, v28, v29
	v_mul_f32_e64 v29, |v28|, s33
	v_exp_f32_e32 v29, v29
	v_fmac_f32_e32 v37, 0x3377d1cf, v36
	v_fmac_f32_e32 v37, 0x3f317217, v36
	v_add_f32_e32 v29, 1.0, v29
	v_mov_b32_e32 v30, v37
	v_sub_f32_e32 v27, v27, v30
	v_log_f32_e32 v36, v29
	v_min_f32_e32 v37, 0, v28
	ds_read_b128 v[28:31], v0 offset:640
	v_fmamk_f32 v26, v26, 0x3d800000, v25
	v_mul_f32_e32 v32, 0x3f317217, v36
	v_fma_f32 v38, v36, s35, -v32
	ds_read_b128 v[32:35], v0 offset:656
	s_waitcnt lgkmcnt(1)
	v_mul_f32_e32 v29, v15, v29
	v_fmac_f32_e32 v29, v12, v28
	v_fmac_f32_e32 v29, v14, v30
	v_fmac_f32_e32 v29, v17, v31
	v_add_f32_e32 v39, v19, v29
	s_waitcnt lgkmcnt(0)
	v_mul_f32_e32 v33, v13, v33
	ds_read_b128 v[28:31], v0 offset:672
	v_fmac_f32_e32 v33, v11, v32
	v_fmac_f32_e32 v33, v9, v34
	v_fmac_f32_e32 v33, v16, v35
	v_add_f32_e32 v39, v39, v33
	ds_read_b128 v[32:35], v0 offset:688
	s_waitcnt lgkmcnt(1)
	v_mul_f32_e32 v29, v7, v29
	v_fmac_f32_e32 v29, v3, v28
	v_fmac_f32_e32 v29, v5, v30
	v_fmac_f32_e32 v29, v10, v31
	v_add_f32_e32 v28, v39, v29
	s_waitcnt lgkmcnt(0)
	v_mul_f32_e32 v29, v4, v33
	v_fmac_f32_e32 v29, v2, v32
	v_fmac_f32_e32 v29, v6, v34
	v_fmac_f32_e32 v29, v8, v35
	v_add_f32_e32 v29, v28, v29
	v_mul_f32_e64 v28, |v29|, s33
	v_exp_f32_e32 v28, v28
	v_fmac_f32_e32 v38, 0x3377d1cf, v36
	v_fmac_f32_e32 v38, 0x3f317217, v36
	v_add_f32_e32 v28, 1.0, v28
	v_mov_b32_e32 v30, v38
	v_min_f32_e32 v29, 0, v29
	v_log_f32_e32 v38, v28
	v_sub_f32_e32 v28, v37, v30
	ds_read_b128 v[30:33], v0 offset:704
	v_fmamk_f32 v27, v27, 0x3d800000, v26
	v_mul_f32_e32 v34, 0x3f317217, v38
	v_fma_f32 v39, v38, s35, -v34
	ds_read_b128 v[34:37], v0 offset:720
	s_waitcnt lgkmcnt(1)
	v_mul_f32_e32 v31, v15, v31
	v_fmac_f32_e32 v31, v12, v30
	v_fmac_f32_e32 v31, v14, v32
	v_fmac_f32_e32 v31, v17, v33
	v_add_f32_e32 v40, v19, v31
	s_waitcnt lgkmcnt(0)
	v_mul_f32_e32 v35, v13, v35
	ds_read_b128 v[30:33], v0 offset:736
	v_fmac_f32_e32 v35, v11, v34
	v_fmac_f32_e32 v35, v9, v36
	v_fmac_f32_e32 v35, v16, v37
	v_add_f32_e32 v40, v40, v35
	ds_read_b128 v[34:37], v0 offset:752
	s_waitcnt lgkmcnt(1)
	v_mul_f32_e32 v31, v7, v31
	v_fmac_f32_e32 v31, v3, v30
	v_fmac_f32_e32 v31, v5, v32
	v_fmac_f32_e32 v31, v10, v33
	v_add_f32_e32 v30, v40, v31
	s_waitcnt lgkmcnt(0)
	v_mul_f32_e32 v31, v4, v35
	v_fmac_f32_e32 v31, v2, v34
	v_fmac_f32_e32 v31, v6, v36
	v_fmac_f32_e32 v31, v8, v37
	v_add_f32_e32 v30, v30, v31
	v_mul_f32_e64 v31, |v30|, s33
	v_exp_f32_e32 v31, v31
	v_fmac_f32_e32 v39, 0x3377d1cf, v38
	v_fmac_f32_e32 v39, 0x3f317217, v38
	v_add_f32_e32 v31, 1.0, v31
	v_mov_b32_e32 v32, v39
	v_sub_f32_e32 v29, v29, v32
	v_log_f32_e32 v38, v31
	v_min_f32_e32 v39, 0, v30
	ds_read_b128 v[30:33], v0 offset:768
	v_fmamk_f32 v28, v28, 0x3d800000, v27
	v_mul_f32_e32 v34, 0x3f317217, v38
	v_fma_f32 v40, v38, s35, -v34
	ds_read_b128 v[34:37], v0 offset:784
	s_waitcnt lgkmcnt(1)
	v_mul_f32_e32 v31, v15, v31
	v_fmac_f32_e32 v31, v12, v30
	v_fmac_f32_e32 v31, v14, v32
	v_fmac_f32_e32 v31, v17, v33
	v_add_f32_e32 v41, v19, v31
	s_waitcnt lgkmcnt(0)
; #define LAS __attribute__((address_space(3)))
; __device__ __forceinline__ void gla_bcum(KArgs a, int tid, int t0, int h, LAS float* segtot, LAS float* glrs, float (&bc)[32], float& tot) {
;     ...
;     for (int r = 0; r < 32; ++r) { const LAS f32x4* gp = (const LAS f32x4*)(glrs + (seg * 32 + r) * 16);
;         float z = bias;
; #pragma unroll
;         for (int q = 0; q < 4; ++q) { const f32x4 g = gp[q]; z += g[0] * w2r[4 * q] + g[1] * w2r[4 * q + 1] + g[2] * w2r[4 * q + 2] + g[3] * w2r[4 * q + 3]; }
;         const float la = (fminf(z, 0.f) - __logf(1.0f + __expf(-fabsf(z)))) * (1.0f / 16.0f);
;         run += la; bc[r] = run; }
	v_mul_f32_e32 v35, v13, v35
	ds_read_b128 v[30:33], v0 offset:800
	v_fmac_f32_e32 v35, v11, v34
	v_fmac_f32_e32 v35, v9, v36
	v_fmac_f32_e32 v35, v16, v37
	v_add_f32_e32 v41, v41, v35
	ds_read_b128 v[34:37], v0 offset:816
	s_waitcnt lgkmcnt(1)
	v_mul_f32_e32 v31, v7, v31
	v_fmac_f32_e32 v31, v3, v30
	v_fmac_f32_e32 v31, v5, v32
	v_fmac_f32_e32 v31, v10, v33
	v_add_f32_e32 v30, v41, v31
	s_waitcnt lgkmcnt(0)
	v_mul_f32_e32 v31, v4, v35
	v_fmac_f32_e32 v31, v2, v34
	v_fmac_f32_e32 v31, v6, v36
	v_fmac_f32_e32 v31, v8, v37
	v_add_f32_e32 v31, v30, v31
	v_mul_f32_e64 v30, |v31|, s33
	v_exp_f32_e32 v30, v30
	v_fmac_f32_e32 v40, 0x3377d1cf, v38
	v_fmac_f32_e32 v40, 0x3f317217, v38
	v_add_f32_e32 v30, 1.0, v30
	v_mov_b32_e32 v32, v40
	v_min_f32_e32 v31, 0, v31
	v_log_f32_e32 v40, v30
	v_sub_f32_e32 v30, v39, v32
	ds_read_b128 v[32:35], v0 offset:832
	v_fmamk_f32 v29, v29, 0x3d800000, v28
	v_mul_f32_e32 v36, 0x3f317217, v40
	v_fma_f32 v41, v40, s35, -v36
	ds_read_b128 v[36:39], v0 offset:848
	s_waitcnt lgkmcnt(1)
	v_mul_f32_e32 v33, v15, v33
	v_fmac_f32_e32 v33, v12, v32
	v_fmac_f32_e32 v33, v14, v34
	v_fmac_f32_e32 v33, v17, v35
	v_add_f32_e32 v42, v19, v33
	s_waitcnt lgkmcnt(0)
	v_mul_f32_e32 v37, v13, v37
	ds_read_b128 v[32:35], v0 offset:864
	v_fmac_f32_e32 v37, v11, v36
	v_fmac_f32_e32 v37, v9, v38
	v_fmac_f32_e32 v37, v16, v39
	v_add_f32_e32 v42, v42, v37
	ds_read_b128 v[36:39], v0 offset:880
	s_waitcnt lgkmcnt(1)
	v_mul_f32_e32 v33, v7, v33
	v_fmac_f32_e32 v33, v3, v32
	v_fmac_f32_e32 v33, v5, v34
	v_fmac_f32_e32 v33, v10, v35
	v_add_f32_e32 v32, v42, v33
	s_waitcnt lgkmcnt(0)
	v_mul_f32_e32 v33, v4, v37
	v_fmac_f32_e32 v33, v2, v36
	v_fmac_f32_e32 v33, v6, v38
	v_fmac_f32_e32 v33, v8, v39
	v_add_f32_e32 v32, v32, v33
	v_mul_f32_e64 v33, |v32|, s33
	v_exp_f32_e32 v33, v33
	v_fmac_f32_e32 v41, 0x3377d1cf, v40
	v_fmac_f32_e32 v41, 0x3f317217, v40
	v_add_f32_e32 v33, 1.0, v33
	v_mov_b32_e32 v34, v41
	v_sub_f32_e32 v31, v31, v34
	v_log_f32_e32 v40, v33
	v_min_f32_e32 v41, 0, v32
	ds_read_b128 v[32:35], v0 offset:896
	v_fmamk_f32 v30, v30, 0x3d800000, v29
	v_mul_f32_e32 v36, 0x3f317217, v40
	v_fma_f32 v42, v40, s35, -v36
	ds_read_b128 v[36:39], v0 offset:912
	s_waitcnt lgkmcnt(1)
	v_mul_f32_e32 v33, v15, v33
	v_fmac_f32_e32 v33, v12, v32
	v_fmac_f32_e32 v33, v14, v34
	v_fmac_f32_e32 v33, v17, v35
	v_add_f32_e32 v43, v19, v33
	s_waitcnt lgkmcnt(0)
	v_mul_f32_e32 v37, v13, v37
	ds_read_b128 v[32:35], v0 offset:928
	v_fmac_f32_e32 v37, v11, v36
	v_fmac_f32_e32 v37, v9, v38
	v_fmac_f32_e32 v37, v16, v39
	v_add_f32_e32 v43, v43, v37
	ds_read_b128 v[36:39], v0 offset:944
	s_waitcnt lgkmcnt(1)
	v_mul_f32_e32 v33, v7, v33
	v_fmac_f32_e32 v33, v3, v32
	v_fmac_f32_e32 v33, v5, v34
	v_fmac_f32_e32 v33, v10, v35
	v_add_f32_e32 v32, v43, v33
	s_waitcnt lgkmcnt(0)
	v_mul_f32_e32 v33, v4, v37
	v_fmac_f32_e32 v33, v2, v36
	v_fmac_f32_e32 v33, v6, v38
	v_fmac_f32_e32 v33, v8, v39
	v_add_f32_e32 v33, v32, v33
	v_mul_f32_e64 v32, |v33|, s33
	v_exp_f32_e32 v32, v32
	v_fmac_f32_e32 v42, 0x3377d1cf, v40
	v_fmac_f32_e32 v42, 0x3f317217, v40
	v_add_f32_e32 v32, 1.0, v32
	v_mov_b32_e32 v34, v42
	v_min_f32_e32 v33, 0, v33
	v_log_f32_e32 v42, v32
	v_sub_f32_e32 v32, v41, v34
	ds_read_b128 v[34:37], v0 offset:960
	v_fmamk_f32 v31, v31, 0x3d800000, v30
	v_mul_f32_e32 v38, 0x3f317217, v42
	v_fma_f32 v43, v42, s35, -v38
	ds_read_b128 v[38:41], v0 offset:976
	s_waitcnt lgkmcnt(1)
	v_mul_f32_e32 v35, v15, v35
	v_fmac_f32_e32 v35, v12, v34
	v_fmac_f32_e32 v35, v14, v36
	v_fmac_f32_e32 v35, v17, v37
	v_add_f32_e32 v44, v19, v35
	s_waitcnt lgkmcnt(0)
	v_mul_f32_e32 v39, v13, v39
	ds_read_b128 v[34:37], v0 offset:992
	v_fmac_f32_e32 v39, v11, v38
	v_fmac_f32_e32 v39, v9, v40
	v_fmac_f32_e32 v39, v16, v41
	v_add_f32_e32 v44, v44, v39
	ds_read_b128 v[38:41], v0 offset:1008
	s_waitcnt lgkmcnt(1)
	v_mul_f32_e32 v35, v7, v35
	v_fmac_f32_e32 v35, v3, v34
	v_fmac_f32_e32 v35, v5, v36
	v_fmac_f32_e32 v35, v10, v37
	v_add_f32_e32 v34, v44, v35
	s_waitcnt lgkmcnt(0)
	v_mul_f32_e32 v35, v4, v39
	v_fmac_f32_e32 v35, v2, v38
	v_fmac_f32_e32 v35, v6, v40
	v_fmac_f32_e32 v35, v8, v41
	v_add_f32_e32 v34, v34, v35
	v_mul_f32_e64 v35, |v34|, s33
	v_exp_f32_e32 v35, v35
	v_fmac_f32_e32 v43, 0x3377d1cf, v42
	v_fmac_f32_e32 v43, 0x3f317217, v42
	v_add_f32_e32 v35, 1.0, v35
	v_mov_b32_e32 v36, v43
	v_sub_f32_e32 v33, v33, v36
	v_log_f32_e32 v42, v35
	v_min_f32_e32 v43, 0, v34
	ds_read_b128 v[34:37], v0 offset:1024
	v_fmamk_f32 v32, v32, 0x3d800000, v31
	v_mul_f32_e32 v38, 0x3f317217, v42
	v_fma_f32 v44, v42, s35, -v38
	ds_read_b128 v[38:41], v0 offset:1040
	s_waitcnt lgkmcnt(1)
	v_mul_f32_e32 v35, v15, v35
	v_fmac_f32_e32 v35, v12, v34
	v_fmac_f32_e32 v35, v14, v36
	v_fmac_f32_e32 v35, v17, v37
	v_add_f32_e32 v45, v19, v35
	s_waitcnt lgkmcnt(0)
	v_mul_f32_e32 v39, v13, v39
	ds_read_b128 v[34:37], v0 offset:1056
	v_fmac_f32_e32 v39, v11, v38
	v_fmac_f32_e32 v39, v9, v40
	v_fmac_f32_e32 v39, v16, v41
	v_add_f32_e32 v45, v45, v39
	ds_read_b128 v[38:41], v0 offset:1072
	s_waitcnt lgkmcnt(1)
	v_mul_f32_e32 v35, v7, v35
	v_fmac_f32_e32 v35, v3, v34
	v_fmac_f32_e32 v35, v5, v36
	v_fmac_f32_e32 v35, v10, v37
	v_add_f32_e32 v34, v45, v35
	s_waitcnt lgkmcnt(0)
	v_mul_f32_e32 v35, v4, v39
	v_fmac_f32_e32 v35, v2, v38
	v_fmac_f32_e32 v35, v6, v40
	v_fmac_f32_e32 v35, v8, v41
	v_add_f32_e32 v35, v34, v35
	v_mul_f32_e64 v34, |v35|, s33
	v_exp_f32_e32 v34, v34
	v_fmac_f32_e32 v44, 0x3377d1cf, v42
	v_fmac_f32_e32 v44, 0x3f317217, v42
	v_add_f32_e32 v34, 1.0, v34
	v_mov_b32_e32 v36, v44
	v_min_f32_e32 v35, 0, v35
	v_log_f32_e32 v44, v34
	v_sub_f32_e32 v34, v43, v36
	ds_read_b128 v[36:39], v0 offset:1088
	v_fmamk_f32 v33, v33, 0x3d800000, v32
	v_mul_f32_e32 v40, 0x3f317217, v44
	v_fma_f32 v45, v44, s35, -v40
	ds_read_b128 v[40:43], v0 offset:1104
	s_waitcnt lgkmcnt(1)
; #define LAS __attribute__((address_space(3)))
; __device__ __forceinline__ void gla_bcum(KArgs a, int tid, int t0, int h, LAS float* segtot, LAS float* glrs, float (&bc)[32], float& tot) {
;     ...
;     for (int r = 0; r < 32; ++r) { const LAS f32x4* gp = (const LAS f32x4*)(glrs + (seg * 32 + r) * 16);
;         float z = bias;
; #pragma unroll
;         for (int q = 0; q < 4; ++q) { const f32x4 g = gp[q]; z += g[0] * w2r[4 * q] + g[1] * w2r[4 * q + 1] + g[2] * w2r[4 * q + 2] + g[3] * w2r[4 * q + 3]; }
;         const float la = (fminf(z, 0.f) - __logf(1.0f + __expf(-fabsf(z)))) * (1.0f / 16.0f);
;         run += la; bc[r] = run; }
	v_mul_f32_e32 v37, v15, v37
	v_fmac_f32_e32 v37, v12, v36
	v_fmac_f32_e32 v37, v14, v38
	v_fmac_f32_e32 v37, v17, v39
	v_add_f32_e32 v46, v19, v37
	s_waitcnt lgkmcnt(0)
	v_mul_f32_e32 v41, v13, v41
	ds_read_b128 v[36:39], v0 offset:1120
	v_fmac_f32_e32 v41, v11, v40
	v_fmac_f32_e32 v41, v9, v42
	v_fmac_f32_e32 v41, v16, v43
	v_add_f32_e32 v46, v46, v41
	ds_read_b128 v[40:43], v0 offset:1136
	s_waitcnt lgkmcnt(1)
	v_mul_f32_e32 v37, v7, v37
	v_fmac_f32_e32 v37, v3, v36
	v_fmac_f32_e32 v37, v5, v38
	v_fmac_f32_e32 v37, v10, v39
	v_add_f32_e32 v36, v46, v37
	s_waitcnt lgkmcnt(0)
	v_mul_f32_e32 v37, v4, v41
	v_fmac_f32_e32 v37, v2, v40
	v_fmac_f32_e32 v37, v6, v42
	v_fmac_f32_e32 v37, v8, v43
	v_add_f32_e32 v36, v36, v37
	v_mul_f32_e64 v37, |v36|, s33
	v_exp_f32_e32 v37, v37
	v_fmac_f32_e32 v45, 0x3377d1cf, v44
	v_fmac_f32_e32 v45, 0x3f317217, v44
	v_add_f32_e32 v37, 1.0, v37
	v_mov_b32_e32 v38, v45
	v_sub_f32_e32 v35, v35, v38
	v_log_f32_e32 v44, v37
	v_min_f32_e32 v45, 0, v36
	ds_read_b128 v[36:39], v0 offset:1152
	v_fmamk_f32 v34, v34, 0x3d800000, v33
	v_mul_f32_e32 v40, 0x3f317217, v44
	v_fma_f32 v46, v44, s35, -v40
	ds_read_b128 v[40:43], v0 offset:1168
	s_waitcnt lgkmcnt(1)
	v_mul_f32_e32 v37, v15, v37
	v_fmac_f32_e32 v37, v12, v36
	v_fmac_f32_e32 v37, v14, v38
	v_fmac_f32_e32 v37, v17, v39
	v_add_f32_e32 v47, v19, v37
	s_waitcnt lgkmcnt(0)
	v_mul_f32_e32 v41, v13, v41
	ds_read_b128 v[36:39], v0 offset:1184
	v_fmac_f32_e32 v41, v11, v40
	v_fmac_f32_e32 v41, v9, v42
	v_fmac_f32_e32 v41, v16, v43
	v_add_f32_e32 v47, v47, v41
	ds_read_b128 v[40:43], v0 offset:1200
	s_waitcnt lgkmcnt(1)
	v_mul_f32_e32 v37, v7, v37
	v_fmac_f32_e32 v37, v3, v36
	v_fmac_f32_e32 v37, v5, v38
	v_fmac_f32_e32 v37, v10, v39
	v_add_f32_e32 v36, v47, v37
	s_waitcnt lgkmcnt(0)
	v_mul_f32_e32 v37, v4, v41
	v_fmac_f32_e32 v37, v2, v40
	v_fmac_f32_e32 v37, v6, v42
	v_fmac_f32_e32 v37, v8, v43
	v_add_f32_e32 v37, v36, v37
	v_mul_f32_e64 v36, |v37|, s33
	v_exp_f32_e32 v36, v36
	v_fmac_f32_e32 v46, 0x3377d1cf, v44
	v_fmac_f32_e32 v46, 0x3f317217, v44
	v_add_f32_e32 v36, 1.0, v36
	v_mov_b32_e32 v38, v46
	v_min_f32_e32 v37, 0, v37
	v_log_f32_e32 v46, v36
	v_sub_f32_e32 v36, v45, v38
	ds_read_b128 v[38:41], v0 offset:1216
	v_fmamk_f32 v35, v35, 0x3d800000, v34
	v_mul_f32_e32 v42, 0x3f317217, v46
	v_fma_f32 v47, v46, s35, -v42
	ds_read_b128 v[42:45], v0 offset:1232
	s_waitcnt lgkmcnt(1)
	v_mul_f32_e32 v39, v15, v39
	v_fmac_f32_e32 v39, v12, v38
	v_fmac_f32_e32 v39, v14, v40
	v_fmac_f32_e32 v39, v17, v41
	v_add_f32_e32 v48, v19, v39
	s_waitcnt lgkmcnt(0)
	v_mul_f32_e32 v43, v13, v43
	ds_read_b128 v[38:41], v0 offset:1248
	v_fmac_f32_e32 v43, v11, v42
	v_fmac_f32_e32 v43, v9, v44
	v_fmac_f32_e32 v43, v16, v45
	v_add_f32_e32 v48, v48, v43
	ds_read_b128 v[42:45], v0 offset:1264
	s_waitcnt lgkmcnt(1)
	v_mul_f32_e32 v39, v7, v39
	v_fmac_f32_e32 v39, v3, v38
	v_fmac_f32_e32 v39, v5, v40
	v_fmac_f32_e32 v39, v10, v41
	v_add_f32_e32 v38, v48, v39
	s_waitcnt lgkmcnt(0)
	v_mul_f32_e32 v39, v4, v43
	v_fmac_f32_e32 v39, v2, v42
	v_fmac_f32_e32 v39, v6, v44
	v_fmac_f32_e32 v39, v8, v45
	v_add_f32_e32 v38, v38, v39
	v_mul_f32_e64 v39, |v38|, s33
	v_exp_f32_e32 v39, v39
	v_fmac_f32_e32 v47, 0x3377d1cf, v46
	v_fmac_f32_e32 v47, 0x3f317217, v46
	v_add_f32_e32 v39, 1.0, v39
	v_mov_b32_e32 v40, v47
	v_sub_f32_e32 v37, v37, v40
	v_log_f32_e32 v46, v39
	v_min_f32_e32 v47, 0, v38
	ds_read_b128 v[38:41], v0 offset:1280
	v_fmamk_f32 v36, v36, 0x3d800000, v35
	v_mul_f32_e32 v42, 0x3f317217, v46
	v_fma_f32 v48, v46, s35, -v42
	ds_read_b128 v[42:45], v0 offset:1296
	s_waitcnt lgkmcnt(1)
	v_mul_f32_e32 v39, v15, v39
	v_fmac_f32_e32 v39, v12, v38
	v_fmac_f32_e32 v39, v14, v40
	v_fmac_f32_e32 v39, v17, v41
	v_add_f32_e32 v49, v19, v39
	s_waitcnt lgkmcnt(0)
	v_mul_f32_e32 v43, v13, v43
	ds_read_b128 v[38:41], v0 offset:1312
	v_fmac_f32_e32 v43, v11, v42
	v_fmac_f32_e32 v43, v9, v44
	v_fmac_f32_e32 v43, v16, v45
	v_add_f32_e32 v49, v49, v43
	ds_read_b128 v[42:45], v0 offset:1328
	s_waitcnt lgkmcnt(1)
	v_mul_f32_e32 v39, v7, v39
	v_fmac_f32_e32 v39, v3, v38
	v_fmac_f32_e32 v39, v5, v40
	v_fmac_f32_e32 v39, v10, v41
	v_add_f32_e32 v38, v49, v39
	s_waitcnt lgkmcnt(0)
	v_mul_f32_e32 v39, v4, v43
	v_fmac_f32_e32 v39, v2, v42
	v_fmac_f32_e32 v39, v6, v44
	v_fmac_f32_e32 v39, v8, v45
	v_add_f32_e32 v39, v38, v39
	v_mul_f32_e64 v38, |v39|, s33
	v_exp_f32_e32 v38, v38
	v_fmac_f32_e32 v48, 0x3377d1cf, v46
	v_fmac_f32_e32 v48, 0x3f317217, v46
	v_add_f32_e32 v38, 1.0, v38
	v_mov_b32_e32 v40, v48
	v_min_f32_e32 v39, 0, v39
	v_log_f32_e32 v48, v38
	v_sub_f32_e32 v38, v47, v40
	ds_read_b128 v[40:43], v0 offset:1344
	v_fmamk_f32 v37, v37, 0x3d800000, v36
	v_mul_f32_e32 v44, 0x3f317217, v48
	v_fma_f32 v49, v48, s35, -v44
	ds_read_b128 v[44:47], v0 offset:1360
	s_waitcnt lgkmcnt(1)
	v_mul_f32_e32 v41, v15, v41
	v_fmac_f32_e32 v41, v12, v40
	v_fmac_f32_e32 v41, v14, v42
	v_fmac_f32_e32 v41, v17, v43
	v_add_f32_e32 v50, v19, v41
	s_waitcnt lgkmcnt(0)
	v_mul_f32_e32 v45, v13, v45
	ds_read_b128 v[40:43], v0 offset:1376
	v_fmac_f32_e32 v45, v11, v44
	v_fmac_f32_e32 v45, v9, v46
	v_fmac_f32_e32 v45, v16, v47
	v_add_f32_e32 v50, v50, v45
	ds_read_b128 v[44:47], v0 offset:1392
	s_waitcnt lgkmcnt(1)
	v_mul_f32_e32 v41, v7, v41
	v_fmac_f32_e32 v41, v3, v40
	v_fmac_f32_e32 v41, v5, v42
	v_fmac_f32_e32 v41, v10, v43
	v_add_f32_e32 v40, v50, v41
	s_waitcnt lgkmcnt(0)
; #define LAS __attribute__((address_space(3)))
; __device__ __forceinline__ void gla_bcum(KArgs a, int tid, int t0, int h, LAS float* segtot, LAS float* glrs, float (&bc)[32], float& tot) {
;     ...
;     for (int r = 0; r < 32; ++r) { const LAS f32x4* gp = (const LAS f32x4*)(glrs + (seg * 32 + r) * 16);
;         float z = bias;
; #pragma unroll
;         for (int q = 0; q < 4; ++q) { const f32x4 g = gp[q]; z += g[0] * w2r[4 * q] + g[1] * w2r[4 * q + 1] + g[2] * w2r[4 * q + 2] + g[3] * w2r[4 * q + 3]; }
;         const float la = (fminf(z, 0.f) - __logf(1.0f + __expf(-fabsf(z)))) * (1.0f / 16.0f);
;         run += la; bc[r] = run; }
	v_mul_f32_e32 v41, v4, v45
	v_fmac_f32_e32 v41, v2, v44
	v_fmac_f32_e32 v41, v6, v46
	v_fmac_f32_e32 v41, v8, v47
	v_add_f32_e32 v40, v40, v41
	v_mul_f32_e64 v41, |v40|, s33
	v_exp_f32_e32 v41, v41
	v_fmac_f32_e32 v49, 0x3377d1cf, v48
	v_fmac_f32_e32 v49, 0x3f317217, v48
	v_add_f32_e32 v41, 1.0, v41
	v_mov_b32_e32 v42, v49
	v_sub_f32_e32 v39, v39, v42
	v_log_f32_e32 v48, v41
	v_min_f32_e32 v49, 0, v40
	ds_read_b128 v[40:43], v0 offset:1408
	v_fmamk_f32 v38, v38, 0x3d800000, v37
	v_mul_f32_e32 v44, 0x3f317217, v48
	v_fma_f32 v50, v48, s35, -v44
	ds_read_b128 v[44:47], v0 offset:1424
	s_waitcnt lgkmcnt(1)
	v_mul_f32_e32 v41, v15, v41
	v_fmac_f32_e32 v41, v12, v40
	v_fmac_f32_e32 v41, v14, v42
	v_fmac_f32_e32 v41, v17, v43
	v_add_f32_e32 v51, v19, v41
	s_waitcnt lgkmcnt(0)
	v_mul_f32_e32 v45, v13, v45
	ds_read_b128 v[40:43], v0 offset:1440
	v_fmac_f32_e32 v45, v11, v44
	v_fmac_f32_e32 v45, v9, v46
	v_fmac_f32_e32 v45, v16, v47
	v_add_f32_e32 v51, v51, v45
	ds_read_b128 v[44:47], v0 offset:1456
	s_waitcnt lgkmcnt(1)
	v_mul_f32_e32 v41, v7, v41
	v_fmac_f32_e32 v41, v3, v40
	v_fmac_f32_e32 v41, v5, v42
	v_fmac_f32_e32 v41, v10, v43
	v_add_f32_e32 v40, v51, v41
	s_waitcnt lgkmcnt(0)
	v_mul_f32_e32 v41, v4, v45
	v_fmac_f32_e32 v41, v2, v44
	v_fmac_f32_e32 v41, v6, v46
	v_fmac_f32_e32 v41, v8, v47
	v_add_f32_e32 v41, v40, v41
	v_mul_f32_e64 v40, |v41|, s33
	v_exp_f32_e32 v40, v40
	v_fmac_f32_e32 v50, 0x3377d1cf, v48
	v_fmac_f32_e32 v50, 0x3f317217, v48
	v_add_f32_e32 v40, 1.0, v40
	v_mov_b32_e32 v42, v50
	v_min_f32_e32 v41, 0, v41
	v_log_f32_e32 v50, v40
	v_sub_f32_e32 v40, v49, v42
	ds_read_b128 v[42:45], v0 offset:1472
	v_fmamk_f32 v39, v39, 0x3d800000, v38
	v_mul_f32_e32 v46, 0x3f317217, v50
	v_fma_f32 v51, v50, s35, -v46
	ds_read_b128 v[46:49], v0 offset:1488
	s_waitcnt lgkmcnt(1)
	v_mul_f32_e32 v43, v15, v43
	v_fmac_f32_e32 v43, v12, v42
	v_fmac_f32_e32 v43, v14, v44
	v_fmac_f32_e32 v43, v17, v45
	v_add_f32_e32 v52, v19, v43
	s_waitcnt lgkmcnt(0)
	v_mul_f32_e32 v47, v13, v47
	ds_read_b128 v[42:45], v0 offset:1504
	v_fmac_f32_e32 v47, v11, v46
	v_fmac_f32_e32 v47, v9, v48
	v_fmac_f32_e32 v47, v16, v49
	v_add_f32_e32 v52, v52, v47
	ds_read_b128 v[46:49], v0 offset:1520
	s_waitcnt lgkmcnt(1)
	v_mul_f32_e32 v43, v7, v43
	v_fmac_f32_e32 v43, v3, v42
	v_fmac_f32_e32 v43, v5, v44
	v_fmac_f32_e32 v43, v10, v45
	v_add_f32_e32 v42, v52, v43
	s_waitcnt lgkmcnt(0)
	v_mul_f32_e32 v43, v4, v47
	v_fmac_f32_e32 v43, v2, v46
	v_fmac_f32_e32 v43, v6, v48
	v_fmac_f32_e32 v43, v8, v49
	v_add_f32_e32 v42, v42, v43
	v_mul_f32_e64 v43, |v42|, s33
	v_exp_f32_e32 v43, v43
	v_fmac_f32_e32 v51, 0x3377d1cf, v50
	v_fmac_f32_e32 v51, 0x3f317217, v50
	v_add_f32_e32 v43, 1.0, v43
	v_mov_b32_e32 v44, v51
	v_sub_f32_e32 v41, v41, v44
	v_log_f32_e32 v50, v43
	v_min_f32_e32 v51, 0, v42
	ds_read_b128 v[42:45], v0 offset:1536
	v_fmamk_f32 v40, v40, 0x3d800000, v39
	v_mul_f32_e32 v46, 0x3f317217, v50
	v_fma_f32 v52, v50, s35, -v46
	ds_read_b128 v[46:49], v0 offset:1552
	s_waitcnt lgkmcnt(1)
	v_mul_f32_e32 v43, v15, v43
	v_fmac_f32_e32 v43, v12, v42
	v_fmac_f32_e32 v43, v14, v44
	v_fmac_f32_e32 v43, v17, v45
	v_add_f32_e32 v53, v19, v43
	s_waitcnt lgkmcnt(0)
	v_mul_f32_e32 v47, v13, v47
	ds_read_b128 v[42:45], v0 offset:1568
	v_fmac_f32_e32 v47, v11, v46
	v_fmac_f32_e32 v47, v9, v48
	v_fmac_f32_e32 v47, v16, v49
	v_add_f32_e32 v53, v53, v47
	ds_read_b128 v[46:49], v0 offset:1584
	s_waitcnt lgkmcnt(1)
	v_mul_f32_e32 v43, v7, v43
	v_fmac_f32_e32 v43, v3, v42
	v_fmac_f32_e32 v43, v5, v44
	v_fmac_f32_e32 v43, v10, v45
	v_add_f32_e32 v42, v53, v43
	s_waitcnt lgkmcnt(0)
	v_mul_f32_e32 v43, v4, v47
	v_fmac_f32_e32 v43, v2, v46
	v_fmac_f32_e32 v43, v6, v48
	v_fmac_f32_e32 v43, v8, v49
	v_add_f32_e32 v43, v42, v43
	v_mul_f32_e64 v42, |v43|, s33
	v_exp_f32_e32 v42, v42
	v_fmac_f32_e32 v52, 0x3377d1cf, v50
	v_fmac_f32_e32 v52, 0x3f317217, v50
	v_add_f32_e32 v42, 1.0, v42
	v_mov_b32_e32 v44, v52
	v_min_f32_e32 v43, 0, v43
	v_log_f32_e32 v52, v42
	v_sub_f32_e32 v42, v51, v44
	ds_read_b128 v[44:47], v0 offset:1600
	v_fmamk_f32 v41, v41, 0x3d800000, v40
	v_mul_f32_e32 v48, 0x3f317217, v52
	v_fma_f32 v53, v52, s35, -v48
	ds_read_b128 v[48:51], v0 offset:1616
	s_waitcnt lgkmcnt(1)
	v_mul_f32_e32 v45, v15, v45
	v_fmac_f32_e32 v45, v12, v44
	v_fmac_f32_e32 v45, v14, v46
	v_fmac_f32_e32 v45, v17, v47
	v_add_f32_e32 v54, v19, v45
	s_waitcnt lgkmcnt(0)
	v_mul_f32_e32 v49, v13, v49
	ds_read_b128 v[44:47], v0 offset:1632
	v_fmac_f32_e32 v49, v11, v48
	v_fmac_f32_e32 v49, v9, v50
	v_fmac_f32_e32 v49, v16, v51
	v_add_f32_e32 v54, v54, v49
	ds_read_b128 v[48:51], v0 offset:1648
	s_waitcnt lgkmcnt(1)
	v_mul_f32_e32 v45, v7, v45
	v_fmac_f32_e32 v45, v3, v44
	v_fmac_f32_e32 v45, v5, v46
	v_fmac_f32_e32 v45, v10, v47
	v_add_f32_e32 v44, v54, v45
	s_waitcnt lgkmcnt(0)
	v_mul_f32_e32 v45, v4, v49
	v_fmac_f32_e32 v45, v2, v48
	v_fmac_f32_e32 v45, v6, v50
	v_fmac_f32_e32 v45, v8, v51
	v_add_f32_e32 v44, v44, v45
	v_mul_f32_e64 v45, |v44|, s33
	v_exp_f32_e32 v45, v45
	v_fmac_f32_e32 v53, 0x3377d1cf, v52
	v_fmac_f32_e32 v53, 0x3f317217, v52
	v_add_f32_e32 v45, 1.0, v45
	v_mov_b32_e32 v46, v53
	v_sub_f32_e32 v43, v43, v46
	v_log_f32_e32 v52, v45
	v_min_f32_e32 v53, 0, v44
	ds_read_b128 v[44:47], v0 offset:1664
	v_fmamk_f32 v42, v42, 0x3d800000, v41
	v_mul_f32_e32 v48, 0x3f317217, v52
	v_fma_f32 v54, v52, s35, -v48
	ds_read_b128 v[48:51], v0 offset:1680
	s_waitcnt lgkmcnt(1)
	v_mul_f32_e32 v45, v15, v45
	v_fmac_f32_e32 v45, v12, v44
	v_fmac_f32_e32 v45, v14, v46
	v_fmac_f32_e32 v45, v17, v47
	v_add_f32_e32 v55, v19, v45
	s_waitcnt lgkmcnt(0)
; #define LAS __attribute__((address_space(3)))
; __device__ __forceinline__ void gla_bcum(KArgs a, int tid, int t0, int h, LAS float* segtot, LAS float* glrs, float (&bc)[32], float& tot) {
;     ...
;     for (int r = 0; r < 32; ++r) { const LAS f32x4* gp = (const LAS f32x4*)(glrs + (seg * 32 + r) * 16);
;         float z = bias;
; #pragma unroll
;         for (int q = 0; q < 4; ++q) { const f32x4 g = gp[q]; z += g[0] * w2r[4 * q] + g[1] * w2r[4 * q + 1] + g[2] * w2r[4 * q + 2] + g[3] * w2r[4 * q + 3]; }
;         const float la = (fminf(z, 0.f) - __logf(1.0f + __expf(-fabsf(z)))) * (1.0f / 16.0f);
;         run += la; bc[r] = run; }
	v_mul_f32_e32 v49, v13, v49
	ds_read_b128 v[44:47], v0 offset:1696
	v_fmac_f32_e32 v49, v11, v48
	v_fmac_f32_e32 v49, v9, v50
	v_fmac_f32_e32 v49, v16, v51
	v_add_f32_e32 v55, v55, v49
	ds_read_b128 v[48:51], v0 offset:1712
	s_waitcnt lgkmcnt(1)
	v_mul_f32_e32 v45, v7, v45
	v_fmac_f32_e32 v45, v3, v44
	v_fmac_f32_e32 v45, v5, v46
	v_fmac_f32_e32 v45, v10, v47
	v_add_f32_e32 v44, v55, v45
	s_waitcnt lgkmcnt(0)
	v_mul_f32_e32 v45, v4, v49
	v_fmac_f32_e32 v45, v2, v48
	v_fmac_f32_e32 v45, v6, v50
	v_fmac_f32_e32 v45, v8, v51
	v_add_f32_e32 v45, v44, v45
	v_mul_f32_e64 v44, |v45|, s33
	v_exp_f32_e32 v44, v44
	v_fmac_f32_e32 v54, 0x3377d1cf, v52
	v_fmac_f32_e32 v54, 0x3f317217, v52
	v_add_f32_e32 v44, 1.0, v44
	v_mov_b32_e32 v46, v54
	v_min_f32_e32 v45, 0, v45
	v_log_f32_e32 v54, v44
	v_sub_f32_e32 v44, v53, v46
	ds_read_b128 v[46:49], v0 offset:1728
	v_fmamk_f32 v43, v43, 0x3d800000, v42
	v_mul_f32_e32 v50, 0x3f317217, v54
	v_fma_f32 v55, v54, s35, -v50
	ds_read_b128 v[50:53], v0 offset:1744
	s_waitcnt lgkmcnt(1)
	v_mul_f32_e32 v47, v15, v47
	v_fmac_f32_e32 v47, v12, v46
	v_fmac_f32_e32 v47, v14, v48
	v_fmac_f32_e32 v47, v17, v49
	v_add_f32_e32 v56, v19, v47
	s_waitcnt lgkmcnt(0)
	v_mul_f32_e32 v51, v13, v51
	ds_read_b128 v[46:49], v0 offset:1760
	v_fmac_f32_e32 v51, v11, v50
	v_fmac_f32_e32 v51, v9, v52
	v_fmac_f32_e32 v51, v16, v53
	v_add_f32_e32 v56, v56, v51
	ds_read_b128 v[50:53], v0 offset:1776
	s_waitcnt lgkmcnt(1)
	v_mul_f32_e32 v47, v7, v47
	v_fmac_f32_e32 v47, v3, v46
	v_fmac_f32_e32 v47, v5, v48
	v_fmac_f32_e32 v47, v10, v49
	v_add_f32_e32 v46, v56, v47
	s_waitcnt lgkmcnt(0)
	v_mul_f32_e32 v47, v4, v51
	v_fmac_f32_e32 v47, v2, v50
	v_fmac_f32_e32 v47, v6, v52
	v_fmac_f32_e32 v47, v8, v53
	v_add_f32_e32 v46, v46, v47
	v_mul_f32_e64 v47, |v46|, s33
	v_exp_f32_e32 v47, v47
	v_fmac_f32_e32 v55, 0x3377d1cf, v54
	v_fmac_f32_e32 v55, 0x3f317217, v54
	v_add_f32_e32 v47, 1.0, v47
	v_mov_b32_e32 v48, v55
	v_sub_f32_e32 v45, v45, v48
	v_log_f32_e32 v54, v47
	v_min_f32_e32 v55, 0, v46
	ds_read_b128 v[46:49], v0 offset:1792
	v_fmamk_f32 v44, v44, 0x3d800000, v43
	v_mul_f32_e32 v50, 0x3f317217, v54
	v_fma_f32 v56, v54, s35, -v50
	ds_read_b128 v[50:53], v0 offset:1808
	s_waitcnt lgkmcnt(1)
	v_mul_f32_e32 v47, v15, v47
	v_fmac_f32_e32 v47, v12, v46
	v_fmac_f32_e32 v47, v14, v48
	v_fmac_f32_e32 v47, v17, v49
	v_add_f32_e32 v57, v19, v47
	s_waitcnt lgkmcnt(0)
	v_mul_f32_e32 v51, v13, v51
	ds_read_b128 v[46:49], v0 offset:1824
	v_fmac_f32_e32 v51, v11, v50
	v_fmac_f32_e32 v51, v9, v52
	v_fmac_f32_e32 v51, v16, v53
	v_add_f32_e32 v57, v57, v51
	ds_read_b128 v[50:53], v0 offset:1840
	s_waitcnt lgkmcnt(1)
	v_mul_f32_e32 v47, v7, v47
	v_fmac_f32_e32 v47, v3, v46
	v_fmac_f32_e32 v47, v5, v48
	v_fmac_f32_e32 v47, v10, v49
	v_add_f32_e32 v46, v57, v47
	s_waitcnt lgkmcnt(0)
	v_mul_f32_e32 v47, v4, v51
	v_fmac_f32_e32 v47, v2, v50
	v_fmac_f32_e32 v47, v6, v52
	v_fmac_f32_e32 v47, v8, v53
	v_add_f32_e32 v46, v46, v47
	v_mul_f32_e64 v47, |v46|, s33
	v_exp_f32_e32 v47, v47
	v_fmac_f32_e32 v56, 0x3377d1cf, v54
	v_fmac_f32_e32 v56, 0x3f317217, v54
	v_add_f32_e32 v47, 1.0, v47
	v_mov_b32_e32 v48, v56
	v_fmamk_f32 v45, v45, 0x3d800000, v44
	v_log_f32_e32 v54, v47
	v_sub_f32_e32 v47, v55, v48
	v_fmamk_f32 v55, v47, 0x3d800000, v45
	v_min_f32_e32 v56, 0, v46
	ds_read_b128 v[46:49], v0 offset:1856
	v_mul_f32_e32 v50, 0x3f317217, v54
	v_fma_f32 v57, v54, s35, -v50
	ds_read_b128 v[50:53], v0 offset:1872
	v_fmac_f32_e32 v57, 0x3377d1cf, v54
	s_waitcnt lgkmcnt(1)
	v_mul_f32_e32 v47, v15, v47
	v_fmac_f32_e32 v47, v12, v46
	v_fmac_f32_e32 v47, v14, v48
	v_fmac_f32_e32 v47, v17, v49
	v_add_f32_e32 v58, v19, v47
	s_waitcnt lgkmcnt(0)
	v_mul_f32_e32 v51, v13, v51
	ds_read_b128 v[46:49], v0 offset:1888
	v_fmac_f32_e32 v51, v11, v50
	v_fmac_f32_e32 v51, v9, v52
	v_fmac_f32_e32 v51, v16, v53
	v_add_f32_e32 v58, v58, v51
	ds_read_b128 v[50:53], v0 offset:1904
	s_waitcnt lgkmcnt(1)
	v_mul_f32_e32 v47, v7, v47
	v_fmac_f32_e32 v47, v3, v46
	v_fmac_f32_e32 v47, v5, v48
	v_fmac_f32_e32 v47, v10, v49
	v_add_f32_e32 v46, v58, v47
	s_waitcnt lgkmcnt(0)
	v_mul_f32_e32 v47, v4, v51
	v_fmac_f32_e32 v47, v2, v50
	v_fmac_f32_e32 v47, v6, v52
	v_fmac_f32_e32 v47, v8, v53
	v_add_f32_e32 v46, v46, v47
	v_mul_f32_e64 v47, |v46|, s33
	v_exp_f32_e32 v47, v47
	v_fmac_f32_e32 v57, 0x3f317217, v54
	v_add_f32_e32 v47, 1.0, v47
	v_mov_b32_e32 v48, v57
	v_min_f32_e32 v57, 0, v46
	v_log_f32_e32 v54, v47
	v_sub_f32_e32 v47, v56, v48
	v_fmamk_f32 v56, v47, 0x3d800000, v55
	ds_read_b128 v[46:49], v0 offset:1920
	v_mul_f32_e32 v50, 0x3f317217, v54
	v_fma_f32 v58, v54, s35, -v50
	ds_read_b128 v[50:53], v0 offset:1936
	v_fmac_f32_e32 v58, 0x3377d1cf, v54
	s_waitcnt lgkmcnt(1)
	v_mul_f32_e32 v47, v15, v47
	v_fmac_f32_e32 v47, v12, v46
	v_fmac_f32_e32 v47, v14, v48
	v_fmac_f32_e32 v47, v17, v49
	v_add_f32_e32 v59, v19, v47
	s_waitcnt lgkmcnt(0)
	v_mul_f32_e32 v51, v13, v51
	ds_read_b128 v[46:49], v0 offset:1952
	v_fmac_f32_e32 v51, v11, v50
	v_fmac_f32_e32 v51, v9, v52
	v_fmac_f32_e32 v51, v16, v53
	v_add_f32_e32 v59, v59, v51
	ds_read_b128 v[50:53], v0 offset:1968
	s_waitcnt lgkmcnt(1)
	v_mul_f32_e32 v47, v7, v47
	v_fmac_f32_e32 v47, v3, v46
	v_fmac_f32_e32 v47, v5, v48
	v_fmac_f32_e32 v47, v10, v49
	v_add_f32_e32 v46, v59, v47
	s_waitcnt lgkmcnt(0)
	v_mul_f32_e32 v47, v4, v51
	v_fmac_f32_e32 v47, v2, v50
	v_fmac_f32_e32 v47, v6, v52
	v_fmac_f32_e32 v47, v8, v53
	v_add_f32_e32 v46, v46, v47
	v_mul_f32_e64 v47, |v46|, s33
	v_exp_f32_e32 v47, v47
	v_fmac_f32_e32 v58, 0x3f317217, v54
	v_add_f32_e32 v47, 1.0, v47
	v_mov_b32_e32 v48, v58
	v_min_f32_e32 v58, 0, v46
	v_log_f32_e32 v54, v47
	v_sub_f32_e32 v47, v57, v48
	v_fmamk_f32 v57, v47, 0x3d800000, v56
	ds_read_b128 v[46:49], v0 offset:1984
	v_mul_f32_e32 v50, 0x3f317217, v54
	v_fma_f32 v59, v54, s35, -v50
	ds_read_b128 v[50:53], v0 offset:2000
	v_fmac_f32_e32 v59, 0x3377d1cf, v54
	s_waitcnt lgkmcnt(1)
; __device__ __forceinline__ float bf2f(bf16_t v) { return __uint_as_float((unsigned)v << 16); }
; __device__ __forceinline__ unsigned f2bf(float f) { return (unsigned)__builtin_bit_cast(unsigned short, (__bf16)f); }
; __device__ __forceinline__ void gla_bcum(KArgs a, int tid, int t0, int h, LAS float* segtot, LAS float* glrs, float (&bc)[32], float& tot) {
;     ...
;     segtot[seg * 128 + d] = run;
;     __syncthreads();
;     float off = 0.f; tot = 0.f;
; #pragma unroll
;     for (int s2 = 0; s2 < 4; ++s2) { const float v = segtot[s2 * 128 + d]; tot += v; if (s2 < seg) off += v; }
; #pragma unroll
;     for (int r = 0; r < 32; ++r) bc[r] += off;
;     ...
;           for (int r = 0; r < 32; ++r) { const int i = seg * 32 + r; const bf16_t* row = proj + (size_t)(t0 + i) * NMAIN + h * 128 + d;
;               const float qv = bf2f(row[C_GQ]), kv = bf2f(row[C_GK]);
;               qgs[i * GP + d] = (bf16_t)f2bf(qv * 0.08838834764831845f * __expf(bc[r])); kgs[i * GP + d] = (bf16_t)f2bf(kv * __expf(-bc[r])); } }
	v_mul_f32_e32 v15, v15, v47
	v_fmac_f32_e32 v15, v12, v46
	v_fmac_f32_e32 v15, v14, v48
	v_fmac_f32_e32 v15, v17, v49
	v_add_f32_e32 v17, v19, v15
	s_waitcnt lgkmcnt(0)
	v_mul_f32_e32 v19, v13, v51
	ds_read_b128 v[12:15], v0 offset:2016
	ds_read_b128 v[46:49], v0 offset:2032
	v_fmac_f32_e32 v19, v11, v50
	v_fmac_f32_e32 v19, v9, v52
	v_fmac_f32_e32 v19, v16, v53
	s_waitcnt lgkmcnt(1)
	v_mul_f32_e32 v0, v7, v13
	v_fmac_f32_e32 v0, v3, v12
	s_waitcnt lgkmcnt(0)
	v_mul_f32_e32 v3, v4, v47
	v_fmac_f32_e32 v0, v5, v14
	v_fmac_f32_e32 v3, v2, v46
	v_add_f32_e32 v9, v17, v19
	v_fmac_f32_e32 v0, v10, v15
	v_fmac_f32_e32 v3, v6, v48
	v_add_f32_e32 v0, v9, v0
	v_fmac_f32_e32 v3, v8, v49
	v_add_f32_e32 v0, v0, v3
	v_mul_f32_e64 v2, |v0|, s33
	v_exp_f32_e32 v2, v2
	v_fmac_f32_e32 v59, 0x3f317217, v54
	v_add_f32_e32 v2, 1.0, v2
	v_mov_b32_e32 v3, v59
	v_sub_f32_e32 v3, v58, v3
	v_log_f32_e32 v2, v2
	v_fmamk_f32 v19, v3, 0x3d800000, v57
	v_min_f32_e32 v0, 0, v0
	v_mul_f32_e32 v3, 0x3f317217, v2
	v_fma_f32 v3, v2, s35, -v3
	v_fmac_f32_e32 v3, 0x3377d1cf, v2
	v_fmac_f32_e32 v3, 0x3f317217, v2
	s_nop 1
	v_mov_b32_e32 v2, v3
	v_sub_f32_e32 v0, v0, v2
	s_and_b32 s6, s36, 0x3fffff80
	v_fmamk_f32 v0, v0, 0x3d800000, v19
	v_lshl_add_u32 v2, s6, 2, v118
	ds_write_b32 v2, v0
	s_waitcnt lgkmcnt(0)
	s_barrier
	v_add_u32_e32 v81, s44, v120
	v_mad_i64_i32 v[188:189], s[100:101], v81, s48, v[82:83]
	global_load_ushort v210, v[188:189], off
	global_load_ushort v211, v[188:189], off offset:1024
	v_add_u32_e32 v81, s44, v122
	v_mad_i64_i32 v[188:189], s[100:101], v81, s48, v[82:83]
	global_load_ushort v212, v[188:189], off
	global_load_ushort v213, v[188:189], off offset:1024
	v_add_u32_e32 v81, s44, v124
	v_mad_i64_i32 v[188:189], s[100:101], v81, s48, v[82:83]
	global_load_ushort v214, v[188:189], off
	global_load_ushort v215, v[188:189], off offset:1024
	v_add_u32_e32 v81, s44, v126
	v_mad_i64_i32 v[188:189], s[100:101], v81, s48, v[82:83]
	global_load_ushort v216, v[188:189], off
	global_load_ushort v217, v[188:189], off offset:1024
	v_add_u32_e32 v81, s44, v128
	v_mad_i64_i32 v[188:189], s[100:101], v81, s48, v[82:83]
	global_load_ushort v218, v[188:189], off
	global_load_ushort v219, v[188:189], off offset:1024
	v_add_u32_e32 v81, s44, v130
	v_mad_i64_i32 v[188:189], s[100:101], v81, s48, v[82:83]
	global_load_ushort v220, v[188:189], off
	global_load_ushort v221, v[188:189], off offset:1024
	v_add_u32_e32 v81, s44, v132
	v_mad_i64_i32 v[188:189], s[100:101], v81, s48, v[82:83]
	global_load_ushort v222, v[188:189], off
	global_load_ushort v223, v[188:189], off offset:1024
	v_add_u32_e32 v81, s44, v134
	v_mad_i64_i32 v[188:189], s[100:101], v81, s48, v[82:83]
	global_load_ushort v224, v[188:189], off
	global_load_ushort v225, v[188:189], off offset:1024
	v_add_u32_e32 v81, s44, v136
	v_mad_i64_i32 v[188:189], s[100:101], v81, s48, v[82:83]
	global_load_ushort v226, v[188:189], off
	global_load_ushort v227, v[188:189], off offset:1024
	v_add_u32_e32 v81, s44, v138
	v_mad_i64_i32 v[188:189], s[100:101], v81, s48, v[82:83]
	global_load_ushort v228, v[188:189], off
	global_load_ushort v229, v[188:189], off offset:1024
	v_add_u32_e32 v81, s44, v140
	v_mad_i64_i32 v[188:189], s[100:101], v81, s48, v[82:83]
	global_load_ushort v230, v[188:189], off
	global_load_ushort v231, v[188:189], off offset:1024
	v_add_u32_e32 v81, s44, v142
	v_mad_i64_i32 v[188:189], s[100:101], v81, s48, v[82:83]
	global_load_ushort v232, v[188:189], off
	global_load_ushort v233, v[188:189], off offset:1024
	v_add_u32_e32 v81, s44, v144
	v_mad_i64_i32 v[188:189], s[100:101], v81, s48, v[82:83]
	global_load_ushort v234, v[188:189], off
	global_load_ushort v235, v[188:189], off offset:1024
	v_add_u32_e32 v81, s44, v146
	v_mad_i64_i32 v[188:189], s[100:101], v81, s48, v[82:83]
	global_load_ushort v236, v[188:189], off
	global_load_ushort v237, v[188:189], off offset:1024
	v_add_u32_e32 v81, s44, v148
	v_mad_i64_i32 v[188:189], s[100:101], v81, s48, v[82:83]
	global_load_ushort v238, v[188:189], off
	global_load_ushort v239, v[188:189], off offset:1024
	v_add_u32_e32 v81, s44, v150
	v_mad_i64_i32 v[188:189], s[100:101], v81, s48, v[82:83]
	global_load_ushort v240, v[188:189], off
	global_load_ushort v241, v[188:189], off offset:1024
	ds_read2st64_b32 v[2:3], v118 offset1:2
	s_cmp_gt_i32 s9, 0
	ds_read2st64_b32 v[4:5], v118 offset0:4 offset1:6
	s_cselect_b64 vcc, -1, 0
	s_cmp_gt_i32 s9, 1
	s_waitcnt lgkmcnt(1)
	v_add_f32_e32 v2, 0, v2
	v_cndmask_b32_e32 v2, 0, v2, vcc
	v_add_f32_e32 v3, v3, v2
	s_cselect_b64 vcc, -1, 0
	v_cndmask_b32_e32 v2, v2, v3, vcc
	s_cmp_gt_i32 s9, 2
	s_waitcnt lgkmcnt(0)
	v_add_f32_e32 v3, v4, v2
	s_cselect_b64 vcc, -1, 0
	s_cmp_gt_i32 s9, 3
	v_cndmask_b32_e32 v6, v2, v3, vcc
	s_cselect_b64 vcc, -1, 0
	s_lshl_b32 s36, s1, 8
	v_lshl_add_u64 v[2:3], v[92:93], 0, s[36:37]
	v_add_f32_e32 v7, v5, v6
	v_cndmask_b32_e32 v50, v6, v7, vcc
	v_add_f32_e32 v53, v18, v50
	v_add_f32_e32 v18, v35, v50
	v_add_f32_e32 v17, v36, v50
	v_add_f32_e32 v54, v20, v50
	v_mul_f32_e32 v20, 0x3fb8aa3b, v53
	v_add_f32_e32 v15, v38, v50
	v_exp_f32_e32 v38, v20
	v_mul_f32_e32 v20, 0xbfb8aa3b, v53
	v_add_f32_e32 v14, v39, v50
	v_exp_f32_e32 v39, v20
	v_add_f32_e32 v58, v21, v50
	v_add_f32_e32 v13, v40, v50
	v_add_f32_e32 v12, v41, v50
	v_add_f32_e32 v4, v19, v50
	v_add_f32_e32 v16, v37, v50
	v_mul_f32_e32 v20, 0x3fb8aa3b, v54
	v_add_f32_e32 v11, v42, v50
	v_add_f32_e32 v10, v43, v50
	v_add_f32_e32 v9, v44, v50
	v_add_f32_e32 v8, v45, v50
	v_add_f32_e32 v22, v22, v50
	v_add_f32_e32 v23, v23, v50
	v_add_f32_e32 v24, v24, v50
	v_add_f32_e32 v25, v25, v50
	v_add_f32_e32 v26, v26, v50
	v_add_f32_e32 v27, v27, v50
	v_add_f32_e32 v28, v28, v50
	v_add_f32_e32 v29, v29, v50
	v_add_f32_e32 v30, v30, v50
	v_add_f32_e32 v31, v31, v50
	v_add_f32_e32 v32, v32, v50
	v_add_f32_e32 v33, v33, v50
	v_add_f32_e32 v34, v34, v50
	s_mov_b32 s9, s37
	v_add_f32_e32 v7, v55, v50
	v_add_f32_e32 v6, v56, v50
	v_add_f32_e32 v5, v57, v50
	v_add_f32_e32 v0, v50, v0
	s_andn2_b64 vcc, exec, s[38:39]
	s_waitcnt vmcnt(31)
; __device__ __forceinline__ float bf2f(bf16_t v) { return __uint_as_float((unsigned)v << 16); }
; __device__ __forceinline__ unsigned f2bf(float f) { return (unsigned)__builtin_bit_cast(unsigned short, (__bf16)f); }
; __device__ __forceinline__ void gla_stage_vT(const bf16_t* proj, int tid, int t0, int h, LAS bf16_t* vT) {
;     ...
;     for (int q = 0; q < 8; ++q) { const int i = tid >> 2, c = (tid & 3) + 4 * q;
;         const u32x4 wv = *(const u32x4*)(proj + (size_t)(t0 + i) * NMAIN + C_GV + h * 256 + 8 * c);
;     ...
;           for (int r = 0; r < 32; ++r) { const int i = seg * 32 + r; const bf16_t* row = proj + (size_t)(t0 + i) * NMAIN + h * 128 + d;
;               const float qv = bf2f(row[C_GQ]), kv = bf2f(row[C_GK]);
;               qgs[i * GP + d] = (bf16_t)f2bf(qv * 0.08838834764831845f * __expf(bc[r])); kgs[i * GP + d] = (bf16_t)f2bf(kv * __expf(-bc[r])); } }
	v_lshlrev_b32_e32 v19, 16, v210
	v_mul_f32_e32 v19, 0x3db504f3, v19
	v_mul_f32_e32 v19, v19, v38
	s_waitcnt vmcnt(30)
	v_lshlrev_b32_e32 v37, 16, v211
	v_cvt_pk_bf16_f32 v19, v19, s0
	ds_write_b16 v121, v19
	v_mul_f32_e32 v19, v39, v37
	v_exp_f32_e32 v38, v20
	v_mul_f32_e32 v20, 0xbfb8aa3b, v54
	v_cvt_pk_bf16_f32 v19, v19, s0
	v_exp_f32_e32 v39, v20
	ds_write_b16 v121, v19 offset:34816
	s_waitcnt vmcnt(29)
	v_lshlrev_b32_e32 v19, 16, v212
	v_mul_f32_e32 v19, 0x3db504f3, v19
	v_mul_f32_e32 v19, v38, v19
	s_waitcnt vmcnt(28)
	v_lshlrev_b32_e32 v37, 16, v213
	v_cvt_pk_bf16_f32 v19, v19, s0
	v_mul_f32_e32 v20, 0x3fb8aa3b, v58
	ds_write_b16 v123, v19
	v_mul_f32_e32 v19, v39, v37
	v_exp_f32_e32 v38, v20
	v_mul_f32_e32 v20, 0xbfb8aa3b, v58
	v_cvt_pk_bf16_f32 v19, v19, s0
	v_exp_f32_e32 v39, v20
	ds_write_b16 v123, v19 offset:34816
	s_waitcnt vmcnt(27)
	v_lshlrev_b32_e32 v19, 16, v214
	v_mul_f32_e32 v19, 0x3db504f3, v19
	v_mul_f32_e32 v19, v38, v19
	s_waitcnt vmcnt(26)
	v_lshlrev_b32_e32 v37, 16, v215
	v_cvt_pk_bf16_f32 v19, v19, s0
	v_mul_f32_e32 v20, 0x3fb8aa3b, v22
	ds_write_b16 v125, v19
	v_mul_f32_e32 v19, v39, v37
	v_exp_f32_e32 v38, v20
	v_mul_f32_e32 v20, 0xbfb8aa3b, v22
	v_cvt_pk_bf16_f32 v19, v19, s0
	v_exp_f32_e32 v22, v20
	ds_write_b16 v125, v19 offset:34816
	s_waitcnt vmcnt(25)
	v_lshlrev_b32_e32 v19, 16, v216
	v_mul_f32_e32 v19, 0x3db504f3, v19
	v_mul_f32_e32 v19, v38, v19
	s_waitcnt vmcnt(24)
	v_lshlrev_b32_e32 v37, 16, v217
	v_add_u32_e32 v61, s44, v119
	v_mov_b64_e32 v[188:189], s[22:23]
	v_mad_i64_i32 v[188:189], s[100:101], v61, s48, v[188:189]
	s_mov_b32 s98, s8
	s_mov_b32 s99, 0
	v_lshl_add_u64 v[188:189], v[188:189], 0, s[98:99]
	v_lshl_add_u64 v[188:189], v[188:189], 0, v[110:111]
	global_load_dwordx4 v[242:245], v[188:189], off offset:2048
	global_load_dwordx4 v[246:249], v[188:189], off offset:2112
	global_load_dwordx4 v[250:253], v[188:189], off offset:2176
	global_load_dwordx4 v[62:65], v[188:189], off offset:2240
	global_load_dwordx4 v[66:69], v[188:189], off offset:2304
	global_load_dwordx4 v[70:73], v[188:189], off offset:2368
	global_load_dwordx4 v[74:77], v[188:189], off offset:2432
	global_load_dwordx4 v[78:81], v[188:189], off offset:2496
	v_cvt_pk_bf16_f32 v19, v19, s0
	ds_write_b16 v127, v19
	v_mul_f32_e32 v19, v22, v37
	v_cvt_pk_bf16_f32 v19, v19, s0
	v_mul_f32_e32 v20, 0x3fb8aa3b, v23
	ds_write_b16 v127, v19 offset:34816
	s_waitcnt vmcnt(31)
	v_lshlrev_b32_e32 v19, 16, v218
	v_exp_f32_e32 v35, v20
	v_mul_f32_e32 v20, 0xbfb8aa3b, v23
	v_exp_f32_e32 v23, v20
	s_waitcnt vmcnt(30)
	v_lshlrev_b32_e32 v22, 16, v219
	v_mul_f32_e32 v19, 0x3db504f3, v19
	v_mul_f32_e32 v19, v35, v19
	v_cvt_pk_bf16_f32 v19, v19, s0
	v_mul_f32_e32 v20, 0x3fb8aa3b, v24
	ds_write_b16 v129, v19
	v_mul_f32_e32 v19, v23, v22
	v_exp_f32_e32 v23, v20
	v_mul_f32_e32 v20, 0xbfb8aa3b, v24
	v_cvt_pk_bf16_f32 v19, v19, s0
	v_exp_f32_e32 v24, v20
	ds_write_b16 v129, v19 offset:34816
	s_waitcnt vmcnt(29)
	v_lshlrev_b32_e32 v19, 16, v220
	v_mul_f32_e32 v19, 0x3db504f3, v19
	v_mul_f32_e32 v19, v23, v19
	s_waitcnt vmcnt(28)
	v_lshlrev_b32_e32 v22, 16, v221
	v_cvt_pk_bf16_f32 v19, v19, s0
	v_mul_f32_e32 v20, 0x3fb8aa3b, v25
	ds_write_b16 v131, v19
	v_mul_f32_e32 v19, v24, v22
	v_exp_f32_e32 v23, v20
	v_mul_f32_e32 v20, 0xbfb8aa3b, v25
	v_cvt_pk_bf16_f32 v19, v19, s0
	v_exp_f32_e32 v24, v20
	ds_write_b16 v131, v19 offset:34816
	s_waitcnt vmcnt(27)
	v_lshlrev_b32_e32 v19, 16, v222
	v_mul_f32_e32 v19, 0x3db504f3, v19
	v_mul_f32_e32 v19, v23, v19
	s_waitcnt vmcnt(26)
	v_lshlrev_b32_e32 v22, 16, v223
	v_cvt_pk_bf16_f32 v19, v19, s0
	v_mul_f32_e32 v20, 0x3fb8aa3b, v26
	ds_write_b16 v133, v19
	v_mul_f32_e32 v19, v24, v22
	v_exp_f32_e32 v23, v20
	v_mul_f32_e32 v20, 0xbfb8aa3b, v26
	v_cvt_pk_bf16_f32 v19, v19, s0
	v_exp_f32_e32 v24, v20
	ds_write_b16 v133, v19 offset:34816
	s_waitcnt vmcnt(25)
	v_lshlrev_b32_e32 v19, 16, v224
	v_mul_f32_e32 v19, 0x3db504f3, v19
	v_mul_f32_e32 v19, v23, v19
	s_waitcnt vmcnt(24)
	v_lshlrev_b32_e32 v22, 16, v225
	v_cvt_pk_bf16_f32 v19, v19, s0
	v_mul_f32_e32 v20, 0x3fb8aa3b, v27
	ds_write_b16 v135, v19
	v_mul_f32_e32 v19, v24, v22
	v_exp_f32_e32 v23, v20
	v_mul_f32_e32 v20, 0xbfb8aa3b, v27
	v_cvt_pk_bf16_f32 v19, v19, s0
	v_exp_f32_e32 v24, v20
	ds_write_b16 v135, v19 offset:34816
	s_waitcnt vmcnt(23)
	v_lshlrev_b32_e32 v19, 16, v226
	v_mul_f32_e32 v19, 0x3db504f3, v19
	v_mul_f32_e32 v19, v23, v19
	s_waitcnt vmcnt(22)
	v_lshlrev_b32_e32 v22, 16, v227
	v_cvt_pk_bf16_f32 v19, v19, s0
	v_mul_f32_e32 v20, 0x3fb8aa3b, v28
	ds_write_b16 v137, v19
	v_mul_f32_e32 v19, v24, v22
	v_exp_f32_e32 v23, v20
	v_mul_f32_e32 v20, 0xbfb8aa3b, v28
	v_cvt_pk_bf16_f32 v19, v19, s0
	v_exp_f32_e32 v24, v20
	ds_write_b16 v137, v19 offset:34816
	s_waitcnt vmcnt(21)
	v_lshlrev_b32_e32 v19, 16, v228
	v_mul_f32_e32 v19, 0x3db504f3, v19
	v_mul_f32_e32 v19, v23, v19
	s_waitcnt vmcnt(20)
	v_lshlrev_b32_e32 v22, 16, v229
	v_cvt_pk_bf16_f32 v19, v19, s0
	v_mul_f32_e32 v20, 0x3fb8aa3b, v29
	ds_write_b16 v139, v19
	v_mul_f32_e32 v19, v24, v22
	v_exp_f32_e32 v23, v20
	v_mul_f32_e32 v20, 0xbfb8aa3b, v29
	v_cvt_pk_bf16_f32 v19, v19, s0
	v_exp_f32_e32 v24, v20
	ds_write_b16 v139, v19 offset:34816
	s_waitcnt vmcnt(19)
	v_lshlrev_b32_e32 v19, 16, v230
	v_mul_f32_e32 v19, 0x3db504f3, v19
	v_mul_f32_e32 v19, v23, v19
	s_waitcnt vmcnt(18)
	v_lshlrev_b32_e32 v22, 16, v231
	v_cvt_pk_bf16_f32 v19, v19, s0
	v_mul_f32_e32 v20, 0x3fb8aa3b, v30
	ds_write_b16 v141, v19
	v_mul_f32_e32 v19, v24, v22
	v_exp_f32_e32 v23, v20
	v_mul_f32_e32 v20, 0xbfb8aa3b, v30
	v_cvt_pk_bf16_f32 v19, v19, s0
	v_exp_f32_e32 v24, v20
	v_add_u32_e32 v20, s44, v152
	ds_write_b16 v141, v19 offset:34816
	v_mad_i64_i32 v[20:21], s[6:7], v20, s48, v[2:3]
	s_waitcnt vmcnt(17)
; __device__ __forceinline__ float bf2f(bf16_t v) { return __uint_as_float((unsigned)v << 16); }
; __device__ __forceinline__ unsigned f2bf(float f) { return (unsigned)__builtin_bit_cast(unsigned short, (__bf16)f); }
;     ...
;           for (int r = 0; r < 32; ++r) { const int i = seg * 32 + r; const bf16_t* row = proj + (size_t)(t0 + i) * NMAIN + h * 128 + d;
;               const float qv = bf2f(row[C_GQ]), kv = bf2f(row[C_GK]);
;               qgs[i * GP + d] = (bf16_t)f2bf(qv * 0.08838834764831845f * __expf(bc[r])); kgs[i * GP + d] = (bf16_t)f2bf(kv * __expf(-bc[r])); } }
	v_lshlrev_b32_e32 v19, 16, v232
	global_load_ushort v25, v[20:21], off
	global_load_ushort v30, v[20:21], off offset:1024
	v_mul_f32_e32 v19, 0x3db504f3, v19
	v_mul_f32_e32 v19, v23, v19
	s_waitcnt vmcnt(18)
	v_lshlrev_b32_e32 v22, 16, v233
	v_cvt_pk_bf16_f32 v19, v19, s0
	v_mul_f32_e32 v20, 0x3fb8aa3b, v31
	ds_write_b16 v143, v19
	v_mul_f32_e32 v19, v24, v22
	v_exp_f32_e32 v23, v20
	v_mul_f32_e32 v20, 0xbfb8aa3b, v31
	v_cvt_pk_bf16_f32 v19, v19, s0
	v_exp_f32_e32 v24, v20
	v_add_u32_e32 v20, s44, v154
	ds_write_b16 v143, v19 offset:34816
	v_mad_i64_i32 v[20:21], s[6:7], v20, s48, v[2:3]
	s_waitcnt vmcnt(17)
	v_lshlrev_b32_e32 v19, 16, v234
	global_load_ushort v26, v[20:21], off
	global_load_ushort v31, v[20:21], off offset:1024
	v_mul_f32_e32 v19, 0x3db504f3, v19
	v_mul_f32_e32 v19, v23, v19
	s_waitcnt vmcnt(18)
	v_lshlrev_b32_e32 v22, 16, v235
	v_cvt_pk_bf16_f32 v19, v19, s0
	v_mul_f32_e32 v20, 0x3fb8aa3b, v32
	ds_write_b16 v145, v19
	v_mul_f32_e32 v19, v24, v22
	v_exp_f32_e32 v23, v20
	v_mul_f32_e32 v20, 0xbfb8aa3b, v32
	v_cvt_pk_bf16_f32 v19, v19, s0
	v_exp_f32_e32 v24, v20
	v_add_u32_e32 v20, s44, v156
	ds_write_b16 v145, v19 offset:34816
	v_mad_i64_i32 v[20:21], s[6:7], v20, s48, v[2:3]
	s_waitcnt vmcnt(17)
	v_lshlrev_b32_e32 v19, 16, v236
	global_load_ushort v27, v[20:21], off
	global_load_ushort v32, v[20:21], off offset:1024
	v_mul_f32_e32 v19, 0x3db504f3, v19
	v_mul_f32_e32 v19, v23, v19
	s_waitcnt vmcnt(18)
	v_lshlrev_b32_e32 v22, 16, v237
	v_cvt_pk_bf16_f32 v19, v19, s0
	v_mul_f32_e32 v20, 0x3fb8aa3b, v33
	ds_write_b16 v147, v19
	v_mul_f32_e32 v19, v24, v22
	v_exp_f32_e32 v23, v20
	v_cvt_pk_bf16_f32 v19, v19, s0
	v_mul_f32_e32 v20, 0xbfb8aa3b, v33
	ds_write_b16 v147, v19 offset:34816
	s_waitcnt vmcnt(17)
	v_lshlrev_b32_e32 v19, 16, v238
	v_exp_f32_e32 v24, v20
	v_mul_f32_e32 v19, 0x3db504f3, v19
	v_add_u32_e32 v20, s44, v158
	v_mad_i64_i32 v[20:21], s[6:7], v20, s48, v[2:3]
	v_mul_f32_e32 v19, v23, v19
	s_waitcnt vmcnt(16)
	v_lshlrev_b32_e32 v22, 16, v239
	global_load_ushort v28, v[20:21], off
	global_load_ushort v33, v[20:21], off offset:1024
	v_cvt_pk_bf16_f32 v19, v19, s0
	v_mul_f32_e32 v20, 0x3fb8aa3b, v34
	ds_write_b16 v149, v19
	v_mul_f32_e32 v19, v24, v22
	v_exp_f32_e32 v23, v20
	v_mul_f32_e32 v20, 0xbfb8aa3b, v34
	v_cvt_pk_bf16_f32 v19, v19, s0
	v_exp_f32_e32 v24, v20
	v_add_u32_e32 v20, s44, v160
	ds_write_b16 v149, v19 offset:34816
	v_mad_i64_i32 v[20:21], s[6:7], v20, s48, v[2:3]
	s_waitcnt vmcnt(17)
	v_lshlrev_b32_e32 v19, 16, v240
	global_load_ushort v29, v[20:21], off
	s_nop 0
	global_load_ushort v20, v[20:21], off offset:1024
	v_mul_f32_e32 v19, 0x3db504f3, v19
	v_mul_f32_e32 v19, v23, v19
	s_waitcnt vmcnt(18)
	v_lshlrev_b32_e32 v22, 16, v241
	v_cvt_pk_bf16_f32 v19, v19, s0
	ds_write_b16 v151, v19
	v_mul_f32_e32 v19, v24, v22
	v_cvt_pk_bf16_f32 v19, v19, s0
	ds_write_b16 v151, v19 offset:34816
	s_waitcnt vmcnt(9)
	v_lshlrev_b32_e32 v19, 16, v25
	v_mul_f32_e32 v22, 0x3db504f3, v19
	v_mul_f32_e32 v19, 0x3fb8aa3b, v18
	v_mul_f32_e32 v18, 0xbfb8aa3b, v18
	v_exp_f32_e32 v24, v18
	v_add_u32_e32 v18, s44, v162
	v_exp_f32_e32 v23, v19
	v_mad_i64_i32 v[18:19], s[6:7], v18, s48, v[2:3]
	s_waitcnt vmcnt(8)
	v_lshlrev_b32_e32 v21, 16, v30
	global_load_ushort v25, v[18:19], off
	global_load_ushort v30, v[18:19], off offset:1024
	v_mul_f32_e32 v18, v23, v22
	v_cvt_pk_bf16_f32 v18, v18, s0
	ds_write_b16 v153, v18
	v_mul_f32_e32 v18, v24, v21
	v_cvt_pk_bf16_f32 v18, v18, s0
	ds_write_b16 v153, v18 offset:34816
	s_waitcnt vmcnt(9)
	v_lshlrev_b32_e32 v18, 16, v26
	v_mul_f32_e32 v22, 0x3db504f3, v18
	v_mul_f32_e32 v18, 0x3fb8aa3b, v17
	v_exp_f32_e32 v23, v18
	v_mul_f32_e32 v17, 0xbfb8aa3b, v17
	v_exp_f32_e32 v17, v17
	v_add_u32_e32 v18, s44, v164
	v_mad_i64_i32 v[18:19], s[6:7], v18, s48, v[2:3]
	s_waitcnt vmcnt(8)
	v_lshlrev_b32_e32 v21, 16, v31
	global_load_ushort v24, v[18:19], off
	global_load_ushort v26, v[18:19], off offset:1024
	v_mul_f32_e32 v18, v23, v22
	v_cvt_pk_bf16_f32 v18, v18, s0
	v_mul_f32_e32 v17, v17, v21
	ds_write_b16 v155, v18
	v_cvt_pk_bf16_f32 v17, v17, s0
	v_add_u32_e32 v18, s44, v166
	ds_write_b16 v155, v17 offset:34816
	v_mad_i64_i32 v[18:19], s[6:7], v18, s48, v[2:3]
	global_load_ushort v22, v[18:19], off
	s_nop 0
	global_load_ushort v18, v[18:19], off offset:1024
	v_mul_f32_e32 v19, 0x3fb8aa3b, v16
	v_mul_f32_e32 v16, 0xbfb8aa3b, v16
	v_exp_f32_e32 v16, v16
	v_exp_f32_e32 v19, v19
	s_waitcnt vmcnt(11)
	v_lshlrev_b32_e32 v17, 16, v27
	s_waitcnt vmcnt(10)
	v_lshlrev_b32_e32 v21, 16, v32
	v_mul_f32_e32 v17, 0x3db504f3, v17
	v_mul_f32_e32 v16, v16, v21
	v_mul_f32_e32 v17, v19, v17
	v_cvt_pk_bf16_f32 v16, v16, s0
	v_cvt_pk_bf16_f32 v17, v17, s0
	ds_write_b16 v157, v16 offset:34816
	v_add_u32_e32 v16, s44, v168
	ds_write_b16 v157, v17
	v_mad_i64_i32 v[16:17], s[6:7], v16, s48, v[2:3]
	global_load_ushort v23, v[16:17], off
	s_nop 0
	global_load_ushort v16, v[16:17], off offset:1024
	v_mul_f32_e32 v17, 0x3fb8aa3b, v15
	v_mul_f32_e32 v15, 0xbfb8aa3b, v15
	v_exp_f32_e32 v15, v15
	s_waitcnt vmcnt(10)
	v_lshlrev_b32_e32 v21, 16, v33
	v_exp_f32_e32 v17, v17
	v_lshlrev_b32_e32 v19, 16, v28
	v_mul_f32_e32 v15, v15, v21
	v_cvt_pk_bf16_f32 v15, v15, s0
	v_mul_f32_e32 v19, 0x3db504f3, v19
	ds_write_b16 v159, v15 offset:34816
	v_mul_f32_e32 v17, v17, v19
	v_cvt_pk_bf16_f32 v17, v17, s0
	ds_write_b16 v159, v17
	s_waitcnt vmcnt(9)
	v_lshlrev_b32_e32 v15, 16, v29
	v_mul_f32_e32 v19, 0x3db504f3, v15
	v_mul_f32_e32 v15, 0x3fb8aa3b, v14
	v_mul_f32_e32 v14, 0xbfb8aa3b, v14
	v_exp_f32_e32 v21, v14
	v_add_u32_e32 v14, s44, v170
	s_waitcnt vmcnt(8)
; #define LAS __attribute__((address_space(3)))
; __device__ __forceinline__ float bf2f(bf16_t v) { return __uint_as_float((unsigned)v << 16); }
; __device__ __forceinline__ unsigned f2bf(float f) { return (unsigned)__builtin_bit_cast(unsigned short, (__bf16)f); }
; __device__ __forceinline__ void gla_stage_vT(const bf16_t* proj, int tid, int t0, int h, LAS bf16_t* vT) {
;     ...
;     for (int q = 0; q < 8; ++q) { const int i = tid >> 2, c = (tid & 3) + 4 * q;
;         const u32x4 wv = *(const u32x4*)(proj + (size_t)(t0 + i) * NMAIN + C_GV + h * 256 + 8 * c);
;         LAS bf16_t* vp = vT + (8 * c) * GP + i;
;         vp[0 * GP] = (bf16_t)(wv.x & 0xffff); vp[1 * GP] = (bf16_t)(wv.x >> 16); vp[2 * GP] = (bf16_t)(wv.y & 0xffff); vp[3 * GP] = (bf16_t)(wv.y >> 16);
;         vp[4 * GP] = (bf16_t)(wv.z & 0xffff); vp[5 * GP] = (bf16_t)(wv.z >> 16); vp[6 * GP] = (bf16_t)(wv.w & 0xffff); vp[7 * GP] = (bf16_t)(wv.w >> 16); }
;     ...
;           for (int r = 0; r < 32; ++r) { const int i = seg * 32 + r; const bf16_t* row = proj + (size_t)(t0 + i) * NMAIN + h * 128 + d;
;               const float qv = bf2f(row[C_GQ]), kv = bf2f(row[C_GK]);
;               qgs[i * GP + d] = (bf16_t)f2bf(qv * 0.08838834764831845f * __expf(bc[r])); kgs[i * GP + d] = (bf16_t)f2bf(kv * __expf(-bc[r])); } }
	v_lshlrev_b32_e32 v17, 16, v20
	v_exp_f32_e32 v20, v15
	v_mad_i64_i32 v[14:15], s[6:7], v14, s48, v[2:3]
	global_load_ushort v27, v[14:15], off
	global_load_ushort v28, v[14:15], off offset:1024
	v_mul_f32_e32 v14, v20, v19
	v_cvt_pk_bf16_f32 v14, v14, s0
	ds_write_b16 v161, v14
	v_mul_f32_e32 v14, v21, v17
	v_cvt_pk_bf16_f32 v14, v14, s0
	ds_write_b16 v161, v14 offset:34816
	s_waitcnt vmcnt(9)
	v_lshlrev_b32_e32 v14, 16, v25
	v_mul_f32_e32 v19, 0x3db504f3, v14
	v_mul_f32_e32 v14, 0x3fb8aa3b, v13
	v_exp_f32_e32 v20, v14
	v_add_u32_e32 v14, s44, v172
	v_mad_i64_i32 v[14:15], s[6:7], v14, s48, v[2:3]
	global_load_ushort v21, v[14:15], off
	s_nop 0
	global_load_ushort v14, v[14:15], off offset:1024
	v_mul_f32_e32 v13, 0xbfb8aa3b, v13
	v_exp_f32_e32 v13, v13
	s_waitcnt vmcnt(10)
	v_lshlrev_b32_e32 v17, 16, v30
	v_mul_f32_e32 v15, v20, v19
	v_cvt_pk_bf16_f32 v15, v15, s0
	v_mul_f32_e32 v13, v13, v17
	v_mul_f32_e32 v17, 0x3fb8aa3b, v12
	v_mul_f32_e32 v12, 0xbfb8aa3b, v12
	v_exp_f32_e32 v12, v12
	v_exp_f32_e32 v17, v17
	ds_write_b16 v163, v15
	v_cvt_pk_bf16_f32 v13, v13, s0
	s_waitcnt vmcnt(8)
	v_lshlrev_b32_e32 v15, 16, v26
	ds_write_b16 v163, v13 offset:34816
	v_lshlrev_b32_e32 v13, 16, v24
	v_mul_f32_e32 v12, v12, v15
	v_mul_f32_e32 v13, 0x3db504f3, v13
	v_cvt_pk_bf16_f32 v12, v12, s0
	v_mul_f32_e32 v13, v17, v13
	ds_write_b16 v165, v12 offset:34816
	v_mul_f32_e32 v12, 0x3fb8aa3b, v11
	v_cvt_pk_bf16_f32 v13, v13, s0
	s_waitcnt vmcnt(6)
	v_lshlrev_b32_e32 v17, 16, v18
	v_exp_f32_e32 v18, v12
	v_add_u32_e32 v12, s44, v174
	ds_write_b16 v165, v13
	v_mad_i64_i32 v[12:13], s[6:7], v12, s48, v[2:3]
	global_load_ushort v19, v[12:13], off
	global_load_ushort v20, v[12:13], off offset:1024
	v_mul_f32_e32 v11, 0xbfb8aa3b, v11
	v_exp_f32_e32 v11, v11
	v_lshlrev_b32_e32 v15, 16, v22
	v_mul_f32_e32 v12, 0x3db504f3, v15
	v_mul_f32_e32 v12, v18, v12
	v_cvt_pk_bf16_f32 v12, v12, s0
	v_mul_f32_e32 v11, v11, v17
	ds_write_b16 v167, v12
	v_cvt_pk_bf16_f32 v11, v11, s0
	v_add_u32_e32 v12, s44, v176
	ds_write_b16 v167, v11 offset:34816
	v_mad_i64_i32 v[12:13], s[6:7], v12, s48, v[2:3]
	global_load_ushort v24, v[12:13], off
	global_load_ushort v25, v[12:13], off offset:1024
	s_waitcnt vmcnt(8)
	v_lshlrev_b32_e32 v15, 16, v16
	v_mul_f32_e32 v16, 0x3fb8aa3b, v10
	v_mul_f32_e32 v10, 0xbfb8aa3b, v10
	v_exp_f32_e32 v10, v10
	v_exp_f32_e32 v12, v16
	v_lshlrev_b32_e32 v11, 16, v23
	v_mul_f32_e32 v11, 0x3db504f3, v11
	v_mul_f32_e32 v10, v10, v15
	v_mul_f32_e32 v11, v12, v11
	v_cvt_pk_bf16_f32 v10, v10, s0
	v_cvt_pk_bf16_f32 v11, v11, s0
	ds_write_b16 v169, v10 offset:34816
	v_add_u32_e32 v10, s44, v178
	ds_write_b16 v169, v11
	v_mad_i64_i32 v[10:11], s[6:7], v10, s48, v[2:3]
	global_load_ushort v32, v[10:11], off
	global_load_ushort v33, v[10:11], off offset:1024
	s_waitcnt vmcnt(9)
	v_lshlrev_b32_e32 v10, 16, v27
	v_mul_f32_e32 v13, 0x3db504f3, v10
	v_mul_f32_e32 v10, 0x3fb8aa3b, v9
	v_exp_f32_e32 v15, v10
	v_add_u32_e32 v10, s44, v180
	v_mad_i64_i32 v[10:11], s[6:7], v10, s48, v[2:3]
	global_load_ushort v36, v[10:11], off
	global_load_ushort v37, v[10:11], off offset:1024
	v_mul_f32_e32 v9, 0xbfb8aa3b, v9
	v_exp_f32_e32 v9, v9
	s_waitcnt vmcnt(10)
	v_lshlrev_b32_e32 v12, 16, v28
	v_mul_f32_e32 v10, v15, v13
	v_cvt_pk_bf16_f32 v10, v10, s0
	v_mul_f32_e32 v9, v9, v12
	v_cvt_pk_bf16_f32 v9, v9, s0
	ds_write_b16 v171, v9 offset:34816
	ds_write_b16 v171, v10
	v_mul_f32_e32 v15, 0xbfb8aa3b, v8
	s_waitcnt vmcnt(9)
	v_lshlrev_b32_e32 v9, 16, v21
	v_mul_f32_e32 v13, 0x3db504f3, v9
	v_add_u32_e32 v9, s44, v182
	v_mad_i64_i32 v[2:3], s[6:7], v9, s48, v[2:3]
	global_load_ushort v40, v[2:3], off
	global_load_ushort v41, v[2:3], off offset:1024
	v_mul_f32_e32 v2, 0x3fb8aa3b, v8
	s_waitcnt vmcnt(10)
	v_lshlrev_b32_e32 v12, 16, v14
	v_exp_f32_e32 v14, v2
	v_exp_f32_e32 v15, v15
	v_mul_f32_e32 v13, v14, v13
	v_cvt_pk_bf16_f32 v13, v13, s0
	ds_write_b16 v173, v13
	v_mul_f32_e32 v12, v15, v12
	v_cvt_pk_bf16_f32 v12, v12, s0
	ds_write_b16 v173, v12 offset:34816
	s_waitcnt vmcnt(9)
	v_lshlrev_b32_e32 v16, 16, v19
	v_mul_f32_e32 v21, 0x3db504f3, v16
	v_mul_f32_e32 v16, 0x3fb8aa3b, v7
	v_exp_f32_e32 v22, v16
	v_mul_f32_e32 v7, 0xbfb8aa3b, v7
	v_exp_f32_e32 v7, v7
	v_mul_f32_e32 v21, v22, v21
	s_waitcnt vmcnt(8)
	v_lshlrev_b32_e32 v20, 16, v20
	v_cvt_pk_bf16_f32 v21, v21, s0
	ds_write_b16 v175, v21
	v_mul_f32_e32 v7, v7, v20
	v_cvt_pk_bf16_f32 v7, v7, s0
	ds_write_b16 v175, v7 offset:34816
	v_mul_f32_e32 v7, 0x3fb8aa3b, v6
	v_exp_f32_e32 v7, v7
	s_waitcnt vmcnt(7)
	v_lshlrev_b32_e32 v24, 16, v24
	v_mul_f32_e32 v24, 0x3db504f3, v24
	s_waitcnt vmcnt(6)
	v_lshlrev_b32_e32 v28, 16, v25
	v_mul_f32_e32 v7, v7, v24
	v_mul_f32_e32 v6, 0xbfb8aa3b, v6
	v_exp_f32_e32 v6, v6
	v_cvt_pk_bf16_f32 v7, v7, s0
	ds_write_b16 v177, v7
	v_mul_f32_e32 v6, v6, v28
	v_cvt_pk_bf16_f32 v6, v6, s0
	ds_write_b16 v177, v6 offset:34816
	s_waitcnt vmcnt(5)
	v_lshlrev_b32_e32 v7, 16, v32
	s_waitcnt vmcnt(4)
; #define LAS __attribute__((address_space(3)))
; __device__ __forceinline__ unsigned f2bf(float f) { return (unsigned)__builtin_bit_cast(unsigned short, (__bf16)f); }
; #define X make_ctx(lds_raw)
; __device__ __forceinline__ void gla_stage_vT(const bf16_t* proj, int tid, int t0, int h, LAS bf16_t* vT) {
;     ...
;         LAS bf16_t* vp = vT + (8 * c) * GP + i;
;         vp[0 * GP] = (bf16_t)(wv.x & 0xffff); vp[1 * GP] = (bf16_t)(wv.x >> 16); vp[2 * GP] = (bf16_t)(wv.y & 0xffff); vp[3 * GP] = (bf16_t)(wv.y >> 16);
;         vp[4 * GP] = (bf16_t)(wv.z & 0xffff); vp[5 * GP] = (bf16_t)(wv.z >> 16); vp[6 * GP] = (bf16_t)(wv.w & 0xffff); vp[7 * GP] = (bf16_t)(wv.w >> 16); }
;     ...
;         __syncthreads();
;         bf16x8 afr[4];
; #pragma unroll
;         for (int ks = 0; ks < 4; ++ks) afr[ks] = *(const LAS bf16x8*)(qgs + (i0 + fr) * GP + 32 * ks + 8 * fq);
;         f32x4 acc[16];
; #pragma unroll
;         for (int nt = 0; nt < 16; ++nt) acc[nt] = (f32x4){0.f, 0.f, 0.f, 0.f};
;         for (int jt = 0; jt <= (w | 1); ++jt) {
;             f32x4 att = {0.f, 0.f, 0.f, 0.f};
;             if (jt <= w) {
; #pragma unroll
;                 for (int ks = 0; ks < 4; ++ks) { const bf16x8 bf = *(const LAS bf16x8*)(kgs + (16 * jt + fr) * GP + 32 * ks + 8 * fq); att = __builtin_amdgcn_mfma_f32_16x16x32_bf16(afr[ks], bf, att, 0, 0, 0); }
;             }
; #pragma unroll
;             for (int e = 0; e < 4; ++e) { const int i = i0 + 4 * fq + e, j = 16 * jt + fr; qgs[i * GP + j] = (bf16_t)f2bf(j <= i ? att[e] : 0.f); }
;         }
;         asm volatile("s_waitcnt lgkmcnt(0)" ::: "memory");
;         for (int ks = 0; ks <= (w >> 1); ++ks) { const bf16x8 af = *(const LAS bf16x8*)(qgs + (i0 + fr) * GP + 32 * ks + 8 * fq);
; #pragma unroll
;             for (int nt = 0; nt < 16; ++nt) { const bf16x8 bf = *(const LAS bf16x8*)(vT + (16 * nt + fr) * GP + 32 * ks + 8 * fq); acc[nt] = __builtin_amdgcn_mfma_f32_16x16x32_bf16(af, bf, acc[nt], 0, 0, 0); } }
;         if (n > 0) {
;             __syncthreads();
;             const bf16_t* sb = (const bf16_t*)kvt + (size_t)unit * 32768;
; #pragma unroll
;             for (int q = 0; q < 8; ++q) { const int sidx = X.tid + 512 * q; const u32x4 wv = *(const u32x4*)(sb + (size_t)sidx * 8);
;                 *(LAS u32x4*)(vT + (sidx >> 4) * GP + (sidx & 15) * 8) = wv; }
	v_lshlrev_b32_e32 v38, 16, v33
	v_mul_f32_e32 v6, 0x3fb8aa3b, v5
	v_mul_f32_e32 v5, 0xbfb8aa3b, v5
	v_exp_f32_e32 v6, v6
	v_exp_f32_e32 v5, v5
	v_mul_f32_e32 v7, 0x3db504f3, v7
	v_mul_f32_e32 v6, v6, v7
	v_mul_f32_e32 v5, v5, v38
	v_cvt_pk_bf16_f32 v6, v6, s0
	v_cvt_pk_bf16_f32 v5, v5, s0
	ds_write_b16 v179, v6
	ds_write_b16 v179, v5 offset:34816
	s_waitcnt vmcnt(3)
	v_lshlrev_b32_e32 v5, 16, v36
	s_waitcnt vmcnt(2)
	v_lshlrev_b32_e32 v6, 16, v37
	v_mul_f32_e32 v7, 0x3fb8aa3b, v4
	v_exp_f32_e32 v2, v7
	v_mul_f32_e32 v4, 0xbfb8aa3b, v4
	v_exp_f32_e32 v4, v4
	v_mul_f32_e32 v3, 0x3db504f3, v5
	v_mul_f32_e32 v2, v2, v3
	v_cvt_pk_bf16_f32 v2, v2, s0
	ds_write_b16 v181, v2
	v_mul_f32_e32 v2, v4, v6
	v_mul_f32_e32 v4, 0x3fb8aa3b, v0
	v_mul_f32_e32 v0, 0xbfb8aa3b, v0
	v_exp_f32_e32 v4, v4
	v_exp_f32_e32 v0, v0
	v_cvt_pk_bf16_f32 v2, v2, s0
	ds_write_b16 v181, v2 offset:34816
	s_waitcnt vmcnt(1)
	v_lshlrev_b32_e32 v2, 16, v40
	s_waitcnt vmcnt(0)
	v_lshlrev_b32_e32 v3, 16, v41
	v_mul_f32_e32 v2, 0x3db504f3, v2
	v_mul_f32_e32 v2, v4, v2
	v_mul_f32_e32 v0, v0, v3
	v_cvt_pk_bf16_f32 v2, v2, s0
	v_cvt_pk_bf16_f32 v0, v0, s0
	ds_write_b16 v183, v2
	ds_write_b16 v183, v0 offset:34816
	ds_write_b16 v203, v242
	ds_write_b16_d16_hi v203, v242 offset:272
	ds_write_b16 v203, v243 offset:544
	ds_write_b16_d16_hi v203, v243 offset:816
	ds_write_b16 v203, v244 offset:1088
	ds_write_b16_d16_hi v203, v244 offset:1360
	ds_write_b16 v203, v245 offset:1632
	ds_write_b16_d16_hi v203, v245 offset:1904
	ds_write_b16 v203, v246 offset:8704
	ds_write_b16_d16_hi v203, v246 offset:8976
	ds_write_b16 v203, v247 offset:9248
	ds_write_b16_d16_hi v203, v247 offset:9520
	ds_write_b16 v203, v248 offset:9792
	ds_write_b16_d16_hi v203, v248 offset:10064
	ds_write_b16 v203, v249 offset:10336
	ds_write_b16_d16_hi v203, v249 offset:10608
	ds_write_b16 v203, v250 offset:17408
	ds_write_b16_d16_hi v203, v250 offset:17680
	ds_write_b16 v203, v251 offset:17952
	ds_write_b16_d16_hi v203, v251 offset:18224
	ds_write_b16 v203, v252 offset:18496
	ds_write_b16_d16_hi v203, v252 offset:18768
	ds_write_b16 v203, v253 offset:19040
	ds_write_b16_d16_hi v203, v253 offset:19312
	ds_write_b16 v203, v62 offset:26112
	ds_write_b16_d16_hi v203, v62 offset:26384
	ds_write_b16 v203, v63 offset:26656
	ds_write_b16_d16_hi v203, v63 offset:26928
	ds_write_b16 v203, v64 offset:27200
	ds_write_b16_d16_hi v203, v64 offset:27472
	ds_write_b16 v203, v65 offset:27744
	ds_write_b16_d16_hi v203, v65 offset:28016
	ds_write_b16 v203, v66 offset:34816
	ds_write_b16_d16_hi v203, v66 offset:35088
	ds_write_b16 v203, v67 offset:35360
	ds_write_b16_d16_hi v203, v67 offset:35632
	ds_write_b16 v203, v68 offset:35904
	ds_write_b16_d16_hi v203, v68 offset:36176
	ds_write_b16 v203, v69 offset:36448
	ds_write_b16_d16_hi v203, v69 offset:36720
	ds_write_b16 v203, v70 offset:43520
	ds_write_b16_d16_hi v203, v70 offset:43792
	ds_write_b16 v203, v71 offset:44064
	ds_write_b16_d16_hi v203, v71 offset:44336
	ds_write_b16 v203, v72 offset:44608
	ds_write_b16_d16_hi v203, v72 offset:44880
	ds_write_b16 v203, v73 offset:45152
	ds_write_b16_d16_hi v203, v73 offset:45424
	ds_write_b16 v203, v74 offset:52224
	ds_write_b16_d16_hi v203, v74 offset:52496
	ds_write_b16 v203, v75 offset:52768
	ds_write_b16_d16_hi v203, v75 offset:53040
	ds_write_b16 v203, v76 offset:53312
	ds_write_b16_d16_hi v203, v76 offset:53584
	ds_write_b16 v203, v77 offset:53856
	ds_write_b16_d16_hi v203, v77 offset:54128
	ds_write_b16 v203, v78 offset:60928
	ds_write_b16_d16_hi v203, v78 offset:61200
	ds_write_b16 v203, v79 offset:61472
	ds_write_b16_d16_hi v203, v79 offset:61744
	ds_write_b16 v203, v80 offset:62016
	ds_write_b16_d16_hi v203, v80 offset:62288
	ds_write_b16 v203, v81 offset:62560
	ds_write_b16_d16_hi v203, v81 offset:62832
	s_waitcnt lgkmcnt(0)
	s_barrier
	ds_read_b128 v[80:83], v204
	ds_read_b128 v[76:79], v204 offset:64
	ds_read_b128 v[72:75], v204 offset:128
	ds_read_b128 v[68:71], v204 offset:192
	s_and_b32 s100, s42, 31
	s_cmp_eq_u32 s100, 0
	s_cbranch_scc1 .La3st_skip
	s_lshl_b32 s98, s42, 16
	s_add_u32 s98, s12, s98
	s_addc_u32 s99, s13, 0
	v_lshl_add_u64 v[222:223], s[98:99], 0, v[94:95]
	global_load_dwordx4 v[222:225], v[222:223], off
	v_lshl_add_u64 v[226:227], s[98:99], 0, v[96:97]
	global_load_dwordx4 v[226:229], v[226:227], off
	v_lshl_add_u64 v[230:231], s[98:99], 0, v[98:99]
	global_load_dwordx4 v[230:233], v[230:231], off
	v_lshl_add_u64 v[234:235], s[98:99], 0, v[100:101]
	global_load_dwordx4 v[234:237], v[234:235], off
	v_lshl_add_u64 v[238:239], s[98:99], 0, v[102:103]
	global_load_dwordx4 v[238:241], v[238:239], off
	v_lshl_add_u64 v[242:243], s[98:99], 0, v[104:105]
	global_load_dwordx4 v[242:245], v[242:243], off
	v_lshl_add_u64 v[246:247], s[98:99], 0, v[106:107]
	global_load_dwordx4 v[246:249], v[246:247], off
	v_lshl_add_u64 v[250:251], s[98:99], 0, v[108:109]
	global_load_dwordx4 v[250:253], v[250:251], off
